# prompt attention unit: next-tile global loads hoisted above the MFMAs, ds_read stream pipelined through dead registers
# speedup vs baseline: 1.0008x; 1.0008x over previous
; __device__ __forceinline__ void attn_wg_unit(const Args& args, int l, int u, LAS unsigned char* lds, int tid_in) {
;     ...
;     const int lane = tid & 63, wave = __builtin_amdgcn_readfirstlane(tid >> 6), r32 = lane & 31, hh = lane >> 5;
;     const int panel = u >> 2, head = u & 3, b = panel >> 5, row0 = panel * 256 + 32 * wave;
;     const bf16_t* Kb = (const bf16_t*)(ws + WS_KP) + (size_t)(l * NBATCH + b) * MEMLEN * MW + head * MHD;
;     const bf16_t* Vt = (const bf16_t*)(ws + WS_VTP) + (size_t)((l * NBATCH + b) * MHEADS + head) * MHD * MEMLEN;
;     LAS unsigned char* buf = lds + ATT_LDS;
;     const int kkey = tid & 15, kdch = tid >> 4;
;     const bf16_t* ksrc = Kb + (size_t)kkey * MW + 8 * kdch;
;     const int kdst = (kdch >> 1) * 1024 + (kkey + 32 * (kdch & 1)) * 16;
;     const int vd = tid >> 1, vs = tid & 1;
;     const bf16_t* vsrc = Vt + (size_t)vd * MEMLEN + 16 * vs;
;     const int vdst = ((vd >> 5) * 2 + vs) * 1024 + (vd & 31) * 16;
;     bf16x8 qf[16];
;     { const bf16_t* qp = PROJ + (size_t)(row0 + r32) * INC + C_Q + head * MHD + 8 * hh;
; #pragma unroll
;       for (int ks = 0; ks < 16; ++ks) qf[ks] = *(const bf16x8*)(qp + 16 * ks); }
;     u32x4 s0, s1;
;     s0 = *(const u32x4*)(ksrc); s1 = *(const u32x4*)(ksrc + (size_t)16 * MW);
;     *(LAS u32x4*)(buf + kdst) = s0; *(LAS u32x4*)(buf + kdst + 256) = s1;
;     __syncthreads();
;     f32x16 st[8];
; #pragma unroll
;     for (int kt = 0; kt < 8; ++kt) {
;         if (kt < 7) { s0 = *(const u32x4*)(ksrc + (size_t)(32 * (kt + 1)) * MW); s1 = *(const u32x4*)(ksrc + (size_t)(32 * (kt + 1) + 16) * MW); }
;         else { s0 = *(const u32x4*)(vsrc); s1 = *(const u32x4*)(vsrc + 8); }
;         const LAS unsigned char* cb = buf + (kt & 1) * 16384 + lane * 16;
;         f32x16 acc;
; #pragma unroll
;         for (int i = 0; i < 16; ++i) acc[i] = 0.f;
; #pragma unroll
;         for (int ks = 0; ks < 16; ++ks) { const bf16x8 kf = *(const LAS bf16x8*)(cb + ks * 1024); acc = __builtin_amdgcn_mfma_f32_32x32x16_bf16(kf, qf[ks], acc, 0, 0, 0); }
;         st[kt] = acc;
;         LAS unsigned char* nb = buf + ((kt + 1) & 1) * 16384;
;         if (kt < 7) { *(LAS u32x4*)(nb + kdst) = s0; *(LAS u32x4*)(nb + kdst + 256) = s1; }
;         else { *(LAS u32x4*)(nb + vdst) = (u32x4){s0.x, s0.y, s1.x, s1.y}; *(LAS u32x4*)(nb + vdst + 512) = (u32x4){s0.z, s0.w, s1.z, s1.w}; }
;         __syncthreads();
;     }
.LBB0_646:
	s_waitcnt vmcnt(0)
	v_mov_b32_e32 v7, v0
	s_ashr_i32 s1, s8, 7
	v_readfirstlane_b32 s0, v7
	s_ashr_i32 s0, s0, 1
	s_and_b32 s2, s7, 0xffffff00
	s_andn2_b32 s0, s0, 31
	s_add_i32 s9, s0, s2
	s_add_i32 s2, s1, s6
	s_ashr_i32 s3, s2, 31
	s_and_b32 s4, s8, 3
	s_lshl_b64 s[0:1], s[2:3], 19
	s_add_u32 s0, s84, s0
	s_addc_u32 s1, s38, s1
	s_lshl_b32 s80, s4, 9
	s_add_u32 s0, s0, s80
	s_addc_u32 s1, s1, 0
	s_lshl_b32 s2, s2, 2
	s_or_b32 s2, s2, s4
	v_ashrrev_i32_e32 v2, 4, v7
	v_ashrrev_i32_e32 v8, 1, v7
	s_ashr_i32 s3, s2, 31
	s_waitcnt vmcnt(0)
	v_and_b32_e32 v12, 15, v7
	v_lshlrev_b32_e32 v4, 3, v2
	v_lshlrev_b32_e32 v2, 5, v2
	v_ashrrev_i32_e32 v9, 31, v8
	s_lshl_b64 s[4:5], s[2:3], 17
	v_and_or_b32 v14, v2, 32, v12
	v_and_b32_e32 v15, 1, v7
	s_waitcnt lgkmcnt(0)
	v_lshlrev_b64 v[2:3], 9, v[8:9]
	v_lshrrev_b32_e32 v9, 5, v7
	s_mov_b32 s2, 0x3ffffe
	v_lshlrev_b32_e32 v8, 4, v8
	v_and_or_b32 v16, v9, s2, v15
	v_and_b32_e32 v192, 0x1f0, v8
	v_and_or_b32 v212, v7, 31, s9
	v_mov_b64_e32 v[8:9], s[66:67]
	v_bfe_u32 v10, v7, 5, 1
	v_mad_i64_i32 v[8:9], s[2:3], v212, s48, v[8:9]
	v_lshl_add_u64 v[8:9], v[8:9], 0, s[80:81]
	v_lshlrev_b32_e32 v130, 3, v10
	v_lshlrev_b32_e32 v10, 4, v10
	v_mov_b32_e32 v11, v131
	v_lshl_add_u64 v[8:9], v[8:9], 0, v[10:11]
	v_lshl_add_u64 v[10:11], v[8:9], 0, s[26:27]
	v_add_co_u32_e32 v8, vcc, s16, v8
	v_ashrrev_i32_e32 v5, 31, v4
	s_nop 0
	v_addc_co_u32_e32 v9, vcc, 0, v9, vcc
	global_load_dwordx4 v[114:117], v[8:9], off offset:2048
	global_load_dwordx4 v[188:191], v[10:11], off offset:32
	global_load_dwordx4 v[184:187], v[10:11], off offset:64
	global_load_dwordx4 v[180:183], v[10:11], off offset:96
	global_load_dwordx4 v[176:179], v[10:11], off offset:128
	global_load_dwordx4 v[172:175], v[10:11], off offset:160
	global_load_dwordx4 v[168:171], v[10:11], off offset:192
	global_load_dwordx4 v[164:167], v[10:11], off offset:224
	global_load_dwordx4 v[160:163], v[10:11], off offset:256
	global_load_dwordx4 v[156:159], v[10:11], off offset:288
	global_load_dwordx4 v[152:155], v[10:11], off offset:320
	global_load_dwordx4 v[148:151], v[10:11], off offset:352
	global_load_dwordx4 v[144:147], v[10:11], off offset:384
	global_load_dwordx4 v[140:143], v[10:11], off offset:416
	global_load_dwordx4 v[136:139], v[10:11], off offset:448
	global_load_dwordx4 v[132:135], v[10:11], off offset:480
	v_lshlrev_b32_e32 v8, 11, v12
	v_mov_b32_e32 v9, v131
	v_lshlrev_b32_e32 v13, 5, v7
	s_add_u32 s4, s29, s4
	v_lshl_add_u64 v[8:9], s[0:1], 0, v[8:9]
	s_addc_u32 s5, s49, s5
	v_lshl_add_u64 v[118:119], v[4:5], 1, v[8:9]
	v_and_b32_e32 v4, 0xfffffc00, v13
	v_and_b32_e32 v6, 63, v7
	v_lshl_or_b32 v7, v14, 4, v4
	v_lshl_add_u64 v[2:3], s[4:5], 0, v[2:3]
	v_lshlrev_b32_e32 v4, 5, v15
	v_mov_b32_e32 v5, v131
	v_add_co_u32_e32 v8, vcc, s14, v118
	v_lshl_add_u64 v[214:215], v[2:3], 0, v[4:5]
	global_load_dwordx4 v[2:5], v[118:119], off
	v_addc_co_u32_e32 v9, vcc, 0, v119, vcc
	global_load_dwordx4 v[8:11], v[8:9], off
	v_add_u32_e32 v120, 0, v7
	v_lshl_add_u32 v211, v6, 4, 0
	v_lshlrev_b32_e32 v193, 10, v16
	s_mov_b32 s0, 0x18000
	v_add3_u32 v216, 0, v193, v192
	v_ashrrev_i32_e32 v213, 31, v212
	s_add_i32 s8, s8, s85
	s_add_i32 s7, s7, s96
	s_cmpk_gt_i32 s8, 0xff
	s_waitcnt vmcnt(1)
	ds_write_b128 v120, v[2:5] offset:8192
	s_waitcnt vmcnt(0)
	ds_write_b128 v120, v[8:11] offset:8448
	s_waitcnt lgkmcnt(0)
	s_barrier
	v_add_co_u32_e32 v200, vcc, s0, v118
	s_mov_b32 s0, 0x28000
	s_nop 0
	v_addc_co_u32_e32 v201, vcc, 0, v119, vcc
	v_add_co_u32_e32 v196, vcc, s24, v118
	global_load_dwordx4 v[200:203], v[200:201], off
	s_nop 0
	v_addc_co_u32_e32 v197, vcc, 0, v119, vcc
	global_load_dwordx4 v[196:199], v[196:197], off
	ds_read_b128 v[18:21], v211 offset:8192
	ds_read_b128 v[26:29], v211 offset:9216
	ds_read_b128 v[30:33], v211 offset:10240
	ds_read_b128 v[34:37], v211 offset:11264
	ds_read_b128 v[38:41], v211 offset:12288
	ds_read_b128 v[42:45], v211 offset:13312
	s_waitcnt lgkmcnt(5)
	v_mfma_f32_32x32x16_bf16 v[2:17], v[18:21], v[114:117], 0
	ds_read_b128 v[46:49], v211 offset:14336
	s_waitcnt lgkmcnt(5)
	v_mfma_f32_32x32x16_bf16 v[2:17], v[26:29], v[188:191], v[2:17]
	ds_read_b128 v[50:53], v211 offset:15360
	s_waitcnt lgkmcnt(5)
	v_mfma_f32_32x32x16_bf16 v[2:17], v[30:33], v[184:187], v[2:17]
	ds_read_b128 v[18:21], v211 offset:16384
	s_waitcnt lgkmcnt(5)
	v_mfma_f32_32x32x16_bf16 v[2:17], v[34:37], v[180:183], v[2:17]
	ds_read_b128 v[26:29], v211 offset:17408
	s_waitcnt lgkmcnt(5)
	v_mfma_f32_32x32x16_bf16 v[2:17], v[38:41], v[176:179], v[2:17]
	ds_read_b128 v[30:33], v211 offset:18432
	s_waitcnt lgkmcnt(5)
	v_mfma_f32_32x32x16_bf16 v[2:17], v[42:45], v[172:175], v[2:17]
	ds_read_b128 v[34:37], v211 offset:19456
	s_waitcnt lgkmcnt(5)
	v_mfma_f32_32x32x16_bf16 v[2:17], v[46:49], v[168:171], v[2:17]
	ds_read_b128 v[38:41], v211 offset:20480
	s_waitcnt lgkmcnt(5)
	v_mfma_f32_32x32x16_bf16 v[2:17], v[50:53], v[164:167], v[2:17]
	ds_read_b128 v[42:45], v211 offset:21504
	s_waitcnt lgkmcnt(5)
	v_mfma_f32_32x32x16_bf16 v[2:17], v[18:21], v[160:163], v[2:17]
	ds_read_b128 v[46:49], v211 offset:22528
	s_waitcnt lgkmcnt(5)
	v_mfma_f32_32x32x16_bf16 v[2:17], v[26:29], v[156:159], v[2:17]
	ds_read_b128 v[50:53], v211 offset:23552
	s_waitcnt lgkmcnt(5)
	v_mfma_f32_32x32x16_bf16 v[2:17], v[30:33], v[152:155], v[2:17]
	s_waitcnt lgkmcnt(4)
	v_mfma_f32_32x32x16_bf16 v[2:17], v[34:37], v[148:151], v[2:17]
	s_waitcnt lgkmcnt(3)
	v_mfma_f32_32x32x16_bf16 v[2:17], v[38:41], v[144:147], v[2:17]
	s_waitcnt lgkmcnt(2)
	v_mfma_f32_32x32x16_bf16 v[2:17], v[42:45], v[140:143], v[2:17]
	s_waitcnt lgkmcnt(1)
	v_mfma_f32_32x32x16_bf16 v[2:17], v[46:49], v[136:139], v[2:17]
	s_waitcnt lgkmcnt(0)
	v_mfma_f32_32x32x16_bf16 v[2:17], v[50:53], v[132:135], v[2:17]
	s_waitcnt vmcnt(0)
	ds_write_b128 v120, v[196:199] offset:24576
	ds_write_b128 v120, v[200:203] offset:24832
	s_waitcnt lgkmcnt(0)
	s_barrier
; #define LAS __attribute__((address_space(3)))
; __device__ __forceinline__ void attn_wg_unit(const Args& args, int l, int u, LAS unsigned char* lds, int tid_in) {
;     ...
; #pragma unroll
;     for (int kt = 0; kt < 8; ++kt) {
;         if (kt < 7) { s0 = *(const u32x4*)(ksrc + (size_t)(32 * (kt + 1)) * MW); s1 = *(const u32x4*)(ksrc + (size_t)(32 * (kt + 1) + 16) * MW); }
;         else { s0 = *(const u32x4*)(vsrc); s1 = *(const u32x4*)(vsrc + 8); }
;         const LAS unsigned char* cb = buf + (kt & 1) * 16384 + lane * 16;
;         f32x16 acc;
; #pragma unroll
;         for (int i = 0; i < 16; ++i) acc[i] = 0.f;
; #pragma unroll
;         for (int ks = 0; ks < 16; ++ks) { const bf16x8 kf = *(const LAS bf16x8*)(cb + ks * 1024); acc = __builtin_amdgcn_mfma_f32_32x32x16_bf16(kf, qf[ks], acc, 0, 0, 0); }
;         st[kt] = acc;
;         LAS unsigned char* nb = buf + ((kt + 1) & 1) * 16384;
;         if (kt < 7) { *(LAS u32x4*)(nb + kdst) = s0; *(LAS u32x4*)(nb + kdst + 256) = s1; }
;         else { *(LAS u32x4*)(nb + vdst) = (u32x4){s0.x, s0.y, s1.x, s1.y}; *(LAS u32x4*)(nb + vdst + 512) = (u32x4){s0.z, s0.w, s1.z, s1.w}; }
;         __syncthreads();
;     }
	v_add_co_u32_e32 v200, vcc, s0, v118
	s_mov_b32 s0, 0x38000
	s_nop 0
	v_addc_co_u32_e32 v201, vcc, 0, v119, vcc
	v_add_co_u32_e32 v196, vcc, s17, v118
	global_load_dwordx4 v[200:203], v[200:201], off
	s_nop 0
	v_addc_co_u32_e32 v197, vcc, 0, v119, vcc
	global_load_dwordx4 v[196:199], v[196:197], off
	ds_read_b128 v[34:37], v211 offset:24576
	ds_read_b128 v[42:45], v211 offset:25600
	ds_read_b128 v[46:49], v211 offset:26624
	ds_read_b128 v[50:53], v211 offset:27648
	ds_read_b128 v[54:57], v211 offset:28672
	ds_read_b128 v[58:61], v211 offset:29696
	s_waitcnt lgkmcnt(5)
	v_mfma_f32_32x32x16_bf16 v[18:33], v[34:37], v[114:117], 0
	ds_read_b128 v[62:65], v211 offset:30720
	s_waitcnt lgkmcnt(5)
	v_mfma_f32_32x32x16_bf16 v[18:33], v[42:45], v[188:191], v[18:33]
	ds_read_b128 v[66:69], v211 offset:31744
	s_waitcnt lgkmcnt(5)
	v_mfma_f32_32x32x16_bf16 v[18:33], v[46:49], v[184:187], v[18:33]
	ds_read_b128 v[34:37], v211 offset:32768
	s_waitcnt lgkmcnt(5)
	v_mfma_f32_32x32x16_bf16 v[18:33], v[50:53], v[180:183], v[18:33]
	ds_read_b128 v[42:45], v211 offset:33792
	s_waitcnt lgkmcnt(5)
	v_mfma_f32_32x32x16_bf16 v[18:33], v[54:57], v[176:179], v[18:33]
	ds_read_b128 v[46:49], v211 offset:34816
	s_waitcnt lgkmcnt(5)
	v_mfma_f32_32x32x16_bf16 v[18:33], v[58:61], v[172:175], v[18:33]
	ds_read_b128 v[50:53], v211 offset:35840
	s_waitcnt lgkmcnt(5)
	v_mfma_f32_32x32x16_bf16 v[18:33], v[62:65], v[168:171], v[18:33]
	ds_read_b128 v[54:57], v211 offset:36864
	s_waitcnt lgkmcnt(5)
	v_mfma_f32_32x32x16_bf16 v[18:33], v[66:69], v[164:167], v[18:33]
	ds_read_b128 v[58:61], v211 offset:37888
	s_waitcnt lgkmcnt(5)
	v_mfma_f32_32x32x16_bf16 v[18:33], v[34:37], v[160:163], v[18:33]
	ds_read_b128 v[62:65], v211 offset:38912
	s_waitcnt lgkmcnt(5)
	v_mfma_f32_32x32x16_bf16 v[18:33], v[42:45], v[156:159], v[18:33]
	ds_read_b128 v[66:69], v211 offset:39936
	s_waitcnt lgkmcnt(5)
	v_mfma_f32_32x32x16_bf16 v[18:33], v[46:49], v[152:155], v[18:33]
	s_waitcnt lgkmcnt(4)
	v_mfma_f32_32x32x16_bf16 v[18:33], v[50:53], v[148:151], v[18:33]
	s_waitcnt lgkmcnt(3)
	v_mfma_f32_32x32x16_bf16 v[18:33], v[54:57], v[144:147], v[18:33]
	s_waitcnt lgkmcnt(2)
	v_mfma_f32_32x32x16_bf16 v[18:33], v[58:61], v[140:143], v[18:33]
	s_waitcnt lgkmcnt(1)
	v_mfma_f32_32x32x16_bf16 v[18:33], v[62:65], v[136:139], v[18:33]
	s_waitcnt lgkmcnt(0)
	v_mfma_f32_32x32x16_bf16 v[18:33], v[66:69], v[132:135], v[18:33]
	s_waitcnt vmcnt(0)
	ds_write_b128 v120, v[196:199] offset:8192
	ds_write_b128 v120, v[200:203] offset:8448
	s_waitcnt lgkmcnt(0)
	s_barrier
	v_add_co_u32_e32 v200, vcc, s0, v118
	s_mov_b32 s0, 0x30000
	s_nop 0
	v_addc_co_u32_e32 v201, vcc, 0, v119, vcc
	v_add_co_u32_e32 v196, vcc, s0, v118
	global_load_dwordx4 v[200:203], v[200:201], off
	s_nop 0
	v_addc_co_u32_e32 v197, vcc, 0, v119, vcc
	global_load_dwordx4 v[196:199], v[196:197], off
	ds_read_b128 v[50:53], v211 offset:8192
	ds_read_b128 v[58:61], v211 offset:9216
	ds_read_b128 v[62:65], v211 offset:10240
	ds_read_b128 v[66:69], v211 offset:11264
	ds_read_b128 v[70:73], v211 offset:12288
	ds_read_b128 v[74:77], v211 offset:13312
	s_waitcnt lgkmcnt(5)
	v_mfma_f32_32x32x16_bf16 v[34:49], v[50:53], v[114:117], 0
	ds_read_b128 v[78:81], v211 offset:14336
	s_waitcnt lgkmcnt(5)
	v_mfma_f32_32x32x16_bf16 v[34:49], v[58:61], v[188:191], v[34:49]
	ds_read_b128 v[82:85], v211 offset:15360
	s_waitcnt lgkmcnt(5)
	v_mfma_f32_32x32x16_bf16 v[34:49], v[62:65], v[184:187], v[34:49]
	ds_read_b128 v[50:53], v211 offset:16384
	s_waitcnt lgkmcnt(5)
	v_mfma_f32_32x32x16_bf16 v[34:49], v[66:69], v[180:183], v[34:49]
	ds_read_b128 v[58:61], v211 offset:17408
	s_waitcnt lgkmcnt(5)
	v_mfma_f32_32x32x16_bf16 v[34:49], v[70:73], v[176:179], v[34:49]
	ds_read_b128 v[62:65], v211 offset:18432
	s_waitcnt lgkmcnt(5)
	v_mfma_f32_32x32x16_bf16 v[34:49], v[74:77], v[172:175], v[34:49]
	ds_read_b128 v[66:69], v211 offset:19456
	s_waitcnt lgkmcnt(5)
	v_mfma_f32_32x32x16_bf16 v[34:49], v[78:81], v[168:171], v[34:49]
	ds_read_b128 v[70:73], v211 offset:20480
	s_waitcnt lgkmcnt(5)
	v_mfma_f32_32x32x16_bf16 v[34:49], v[82:85], v[164:167], v[34:49]
	ds_read_b128 v[74:77], v211 offset:21504
	s_waitcnt lgkmcnt(5)
	v_mfma_f32_32x32x16_bf16 v[34:49], v[50:53], v[160:163], v[34:49]
	ds_read_b128 v[78:81], v211 offset:22528
	s_waitcnt lgkmcnt(5)
	v_mfma_f32_32x32x16_bf16 v[34:49], v[58:61], v[156:159], v[34:49]
	ds_read_b128 v[82:85], v211 offset:23552
	s_waitcnt lgkmcnt(5)
	v_mfma_f32_32x32x16_bf16 v[34:49], v[62:65], v[152:155], v[34:49]
	s_waitcnt lgkmcnt(4)
	v_mfma_f32_32x32x16_bf16 v[34:49], v[66:69], v[148:151], v[34:49]
	s_waitcnt lgkmcnt(3)
	v_mfma_f32_32x32x16_bf16 v[34:49], v[70:73], v[144:147], v[34:49]
	s_waitcnt lgkmcnt(2)
	v_mfma_f32_32x32x16_bf16 v[34:49], v[74:77], v[140:143], v[34:49]
	s_waitcnt lgkmcnt(1)
	v_mfma_f32_32x32x16_bf16 v[34:49], v[78:81], v[136:139], v[34:49]
	s_waitcnt lgkmcnt(0)
	v_mfma_f32_32x32x16_bf16 v[34:49], v[82:85], v[132:135], v[34:49]
	s_waitcnt vmcnt(0)
	ds_write_b128 v120, v[196:199] offset:24576
	ds_write_b128 v120, v[200:203] offset:24832
	s_waitcnt lgkmcnt(0)
	s_barrier
; #define LAS __attribute__((address_space(3)))
; __device__ __forceinline__ void attn_wg_unit(const Args& args, int l, int u, LAS unsigned char* lds, int tid_in) {
;     ...
; #pragma unroll
;     for (int kt = 0; kt < 8; ++kt) {
;         if (kt < 7) { s0 = *(const u32x4*)(ksrc + (size_t)(32 * (kt + 1)) * MW); s1 = *(const u32x4*)(ksrc + (size_t)(32 * (kt + 1) + 16) * MW); }
;         else { s0 = *(const u32x4*)(vsrc); s1 = *(const u32x4*)(vsrc + 8); }
;         const LAS unsigned char* cb = buf + (kt & 1) * 16384 + lane * 16;
;         f32x16 acc;
; #pragma unroll
;         for (int i = 0; i < 16; ++i) acc[i] = 0.f;
; #pragma unroll
;         for (int ks = 0; ks < 16; ++ks) { const bf16x8 kf = *(const LAS bf16x8*)(cb + ks * 1024); acc = __builtin_amdgcn_mfma_f32_32x32x16_bf16(kf, qf[ks], acc, 0, 0, 0); }
;         st[kt] = acc;
;         LAS unsigned char* nb = buf + ((kt + 1) & 1) * 16384;
;         if (kt < 7) { *(LAS u32x4*)(nb + kdst) = s0; *(LAS u32x4*)(nb + kdst + 256) = s1; }
;         else { *(LAS u32x4*)(nb + vdst) = (u32x4){s0.x, s0.y, s1.x, s1.y}; *(LAS u32x4*)(nb + vdst + 512) = (u32x4){s0.z, s0.w, s1.z, s1.w}; }
;         __syncthreads();
;     }
	s_mov_b32 s0, 0x48000
	v_add_co_u32_e32 v200, vcc, s0, v118
	s_mov_b32 s0, 0x58000
	s_nop 0
	v_addc_co_u32_e32 v201, vcc, 0, v119, vcc
	v_add_co_u32_e32 v196, vcc, s21, v118
	global_load_dwordx4 v[200:203], v[200:201], off
	s_nop 0
	v_addc_co_u32_e32 v197, vcc, 0, v119, vcc
	global_load_dwordx4 v[196:199], v[196:197], off
	ds_read_b128 v[66:69], v211 offset:24576
	ds_read_b128 v[74:77], v211 offset:25600
	ds_read_b128 v[78:81], v211 offset:26624
	ds_read_b128 v[82:85], v211 offset:27648
	ds_read_b128 v[86:89], v211 offset:28672
	ds_read_b128 v[90:93], v211 offset:29696
	s_waitcnt lgkmcnt(5)
	v_mfma_f32_32x32x16_bf16 v[50:65], v[66:69], v[114:117], 0
	ds_read_b128 v[94:97], v211 offset:30720
	s_waitcnt lgkmcnt(5)
	v_mfma_f32_32x32x16_bf16 v[50:65], v[74:77], v[188:191], v[50:65]
	ds_read_b128 v[98:101], v211 offset:31744
	s_waitcnt lgkmcnt(5)
	v_mfma_f32_32x32x16_bf16 v[50:65], v[78:81], v[184:187], v[50:65]
	ds_read_b128 v[66:69], v211 offset:32768
	s_waitcnt lgkmcnt(5)
	v_mfma_f32_32x32x16_bf16 v[50:65], v[82:85], v[180:183], v[50:65]
	ds_read_b128 v[74:77], v211 offset:33792
	s_waitcnt lgkmcnt(5)
	v_mfma_f32_32x32x16_bf16 v[50:65], v[86:89], v[176:179], v[50:65]
	ds_read_b128 v[78:81], v211 offset:34816
	s_waitcnt lgkmcnt(5)
	v_mfma_f32_32x32x16_bf16 v[50:65], v[90:93], v[172:175], v[50:65]
	ds_read_b128 v[82:85], v211 offset:35840
	s_waitcnt lgkmcnt(5)
	v_mfma_f32_32x32x16_bf16 v[50:65], v[94:97], v[168:171], v[50:65]
	ds_read_b128 v[86:89], v211 offset:36864
	s_waitcnt lgkmcnt(5)
	v_mfma_f32_32x32x16_bf16 v[50:65], v[98:101], v[164:167], v[50:65]
	ds_read_b128 v[90:93], v211 offset:37888
	s_waitcnt lgkmcnt(5)
	v_mfma_f32_32x32x16_bf16 v[50:65], v[66:69], v[160:163], v[50:65]
	ds_read_b128 v[94:97], v211 offset:38912
	s_waitcnt lgkmcnt(5)
	v_mfma_f32_32x32x16_bf16 v[50:65], v[74:77], v[156:159], v[50:65]
	ds_read_b128 v[98:101], v211 offset:39936
	s_waitcnt lgkmcnt(5)
	v_mfma_f32_32x32x16_bf16 v[50:65], v[78:81], v[152:155], v[50:65]
	s_waitcnt lgkmcnt(4)
	v_mfma_f32_32x32x16_bf16 v[50:65], v[82:85], v[148:151], v[50:65]
	s_waitcnt lgkmcnt(3)
	v_mfma_f32_32x32x16_bf16 v[50:65], v[86:89], v[144:147], v[50:65]
	s_waitcnt lgkmcnt(2)
	v_mfma_f32_32x32x16_bf16 v[50:65], v[90:93], v[140:143], v[50:65]
	s_waitcnt lgkmcnt(1)
	v_mfma_f32_32x32x16_bf16 v[50:65], v[94:97], v[136:139], v[50:65]
	s_waitcnt lgkmcnt(0)
	v_mfma_f32_32x32x16_bf16 v[50:65], v[98:101], v[132:135], v[50:65]
	s_waitcnt vmcnt(0)
	ds_write_b128 v120, v[196:199] offset:8192
	ds_write_b128 v120, v[200:203] offset:8448
	s_waitcnt lgkmcnt(0)
	s_barrier
	v_add_co_u32_e32 v200, vcc, s0, v118
	s_mov_b32 s0, 0x50000
	s_nop 0
	v_addc_co_u32_e32 v201, vcc, 0, v119, vcc
	v_add_co_u32_e32 v196, vcc, s0, v118
	global_load_dwordx4 v[200:203], v[200:201], off
	s_nop 0
	v_addc_co_u32_e32 v197, vcc, 0, v119, vcc
	global_load_dwordx4 v[196:199], v[196:197], off
	ds_read_b128 v[82:85], v211 offset:8192
	ds_read_b128 v[90:93], v211 offset:9216
	ds_read_b128 v[94:97], v211 offset:10240
	ds_read_b128 v[98:101], v211 offset:11264
	ds_read_b128 v[102:105], v211 offset:12288
	ds_read_b128 v[106:109], v211 offset:13312
	s_waitcnt lgkmcnt(5)
	v_mfma_f32_32x32x16_bf16 v[66:81], v[82:85], v[114:117], 0
	ds_read_b128 v[110:113], v211 offset:14336
	s_waitcnt lgkmcnt(5)
	v_mfma_f32_32x32x16_bf16 v[66:81], v[90:93], v[188:191], v[66:81]
	ds_read_b128 v[122:125], v211 offset:15360
	s_waitcnt lgkmcnt(5)
	v_mfma_f32_32x32x16_bf16 v[66:81], v[94:97], v[184:187], v[66:81]
	ds_read_b128 v[82:85], v211 offset:16384
	s_waitcnt lgkmcnt(5)
	v_mfma_f32_32x32x16_bf16 v[66:81], v[98:101], v[180:183], v[66:81]
	ds_read_b128 v[90:93], v211 offset:17408
	s_waitcnt lgkmcnt(5)
	v_mfma_f32_32x32x16_bf16 v[66:81], v[102:105], v[176:179], v[66:81]
	ds_read_b128 v[94:97], v211 offset:18432
	s_waitcnt lgkmcnt(5)
	v_mfma_f32_32x32x16_bf16 v[66:81], v[106:109], v[172:175], v[66:81]
	ds_read_b128 v[98:101], v211 offset:19456
	s_waitcnt lgkmcnt(5)
	v_mfma_f32_32x32x16_bf16 v[66:81], v[110:113], v[168:171], v[66:81]
	ds_read_b128 v[102:105], v211 offset:20480
	s_waitcnt lgkmcnt(5)
	v_mfma_f32_32x32x16_bf16 v[66:81], v[122:125], v[164:167], v[66:81]
	ds_read_b128 v[106:109], v211 offset:21504
	s_waitcnt lgkmcnt(5)
	v_mfma_f32_32x32x16_bf16 v[66:81], v[82:85], v[160:163], v[66:81]
	ds_read_b128 v[110:113], v211 offset:22528
	s_waitcnt lgkmcnt(5)
	v_mfma_f32_32x32x16_bf16 v[66:81], v[90:93], v[156:159], v[66:81]
	ds_read_b128 v[122:125], v211 offset:23552
	s_waitcnt lgkmcnt(5)
	v_mfma_f32_32x32x16_bf16 v[66:81], v[94:97], v[152:155], v[66:81]
	s_waitcnt lgkmcnt(4)
	v_mfma_f32_32x32x16_bf16 v[66:81], v[98:101], v[148:151], v[66:81]
	s_waitcnt lgkmcnt(3)
	v_mfma_f32_32x32x16_bf16 v[66:81], v[102:105], v[144:147], v[66:81]
	s_waitcnt lgkmcnt(2)
	v_mfma_f32_32x32x16_bf16 v[66:81], v[106:109], v[140:143], v[66:81]
	s_waitcnt lgkmcnt(1)
	v_mfma_f32_32x32x16_bf16 v[66:81], v[110:113], v[136:139], v[66:81]
	s_waitcnt lgkmcnt(0)
	v_mfma_f32_32x32x16_bf16 v[66:81], v[122:125], v[132:135], v[66:81]
	s_waitcnt vmcnt(0)
	ds_write_b128 v120, v[196:199] offset:24576
	ds_write_b128 v120, v[200:203] offset:24832
	s_waitcnt lgkmcnt(0)
	s_barrier
; #define LAS __attribute__((address_space(3)))
; __device__ __forceinline__ void attn_wg_unit(const Args& args, int l, int u, LAS unsigned char* lds, int tid_in) {
;     ...
; #pragma unroll
;     for (int kt = 0; kt < 8; ++kt) {
;         if (kt < 7) { s0 = *(const u32x4*)(ksrc + (size_t)(32 * (kt + 1)) * MW); s1 = *(const u32x4*)(ksrc + (size_t)(32 * (kt + 1) + 16) * MW); }
;         else { s0 = *(const u32x4*)(vsrc); s1 = *(const u32x4*)(vsrc + 8); }
;         const LAS unsigned char* cb = buf + (kt & 1) * 16384 + lane * 16;
;         f32x16 acc;
; #pragma unroll
;         for (int i = 0; i < 16; ++i) acc[i] = 0.f;
; #pragma unroll
;         for (int ks = 0; ks < 16; ++ks) { const bf16x8 kf = *(const LAS bf16x8*)(cb + ks * 1024); acc = __builtin_amdgcn_mfma_f32_32x32x16_bf16(kf, qf[ks], acc, 0, 0, 0); }
;         st[kt] = acc;
;         LAS unsigned char* nb = buf + ((kt + 1) & 1) * 16384;
;         if (kt < 7) { *(LAS u32x4*)(nb + kdst) = s0; *(LAS u32x4*)(nb + kdst + 256) = s1; }
;         else { *(LAS u32x4*)(nb + vdst) = (u32x4){s0.x, s0.y, s1.x, s1.y}; *(LAS u32x4*)(nb + vdst + 512) = (u32x4){s0.z, s0.w, s1.z, s1.w}; }
;         __syncthreads();
;     }
	s_mov_b32 s0, 0x68000
	v_add_co_u32_e32 v200, vcc, s0, v118
	s_mov_b32 s0, 0x78000
	s_nop 0
	v_addc_co_u32_e32 v201, vcc, 0, v119, vcc
	v_add_co_u32_e32 v196, vcc, s22, v118
	global_load_dwordx4 v[200:203], v[200:201], off
	s_nop 0
	v_addc_co_u32_e32 v197, vcc, 0, v119, vcc
	global_load_dwordx4 v[196:199], v[196:197], off
	ds_read_b128 v[98:101], v211 offset:24576
	ds_read_b128 v[106:109], v211 offset:25600
	ds_read_b128 v[110:113], v211 offset:26624
	ds_read_b128 v[122:125], v211 offset:27648
	ds_read_b128 v[126:129], v211 offset:28672
	ds_read_b128 v[192:195], v211 offset:29696
	s_waitcnt lgkmcnt(5)
	v_mfma_f32_32x32x16_bf16 v[82:97], v[98:101], v[114:117], 0
	ds_read_b128 v[98:101], v211 offset:30720
	s_waitcnt lgkmcnt(5)
	v_mfma_f32_32x32x16_bf16 v[82:97], v[106:109], v[188:191], v[82:97]
	ds_read_b128 v[106:109], v211 offset:31744
	s_waitcnt lgkmcnt(5)
	v_mfma_f32_32x32x16_bf16 v[82:97], v[110:113], v[184:187], v[82:97]
	ds_read_b128 v[110:113], v211 offset:32768
	s_waitcnt lgkmcnt(5)
	v_mfma_f32_32x32x16_bf16 v[82:97], v[122:125], v[180:183], v[82:97]
	ds_read_b128 v[122:125], v211 offset:33792
	s_waitcnt lgkmcnt(5)
	v_mfma_f32_32x32x16_bf16 v[82:97], v[126:129], v[176:179], v[82:97]
	ds_read_b128 v[126:129], v211 offset:34816
	s_waitcnt lgkmcnt(5)
	v_mfma_f32_32x32x16_bf16 v[82:97], v[192:195], v[172:175], v[82:97]
	ds_read_b128 v[192:195], v211 offset:35840
	s_waitcnt lgkmcnt(5)
	v_mfma_f32_32x32x16_bf16 v[82:97], v[98:101], v[168:171], v[82:97]
	ds_read_b128 v[98:101], v211 offset:36864
	s_waitcnt lgkmcnt(5)
	v_mfma_f32_32x32x16_bf16 v[82:97], v[106:109], v[164:167], v[82:97]
	ds_read_b128 v[106:109], v211 offset:37888
	s_waitcnt lgkmcnt(5)
	v_mfma_f32_32x32x16_bf16 v[82:97], v[110:113], v[160:163], v[82:97]
	ds_read_b128 v[110:113], v211 offset:38912
	s_waitcnt lgkmcnt(5)
	v_mfma_f32_32x32x16_bf16 v[82:97], v[122:125], v[156:159], v[82:97]
	ds_read_b128 v[122:125], v211 offset:39936
	s_waitcnt lgkmcnt(5)
	v_mfma_f32_32x32x16_bf16 v[82:97], v[126:129], v[152:155], v[82:97]
	s_waitcnt lgkmcnt(4)
	v_mfma_f32_32x32x16_bf16 v[82:97], v[192:195], v[148:151], v[82:97]
	s_waitcnt lgkmcnt(3)
	v_mfma_f32_32x32x16_bf16 v[82:97], v[98:101], v[144:147], v[82:97]
	s_waitcnt lgkmcnt(2)
	v_mfma_f32_32x32x16_bf16 v[82:97], v[106:109], v[140:143], v[82:97]
	s_waitcnt lgkmcnt(1)
	v_mfma_f32_32x32x16_bf16 v[82:97], v[110:113], v[136:139], v[82:97]
	s_waitcnt lgkmcnt(0)
	v_mfma_f32_32x32x16_bf16 v[82:97], v[122:125], v[132:135], v[82:97]
	s_waitcnt vmcnt(0)
	ds_write_b128 v120, v[196:199] offset:8192
	ds_write_b128 v120, v[200:203] offset:8448
	s_waitcnt lgkmcnt(0)
	s_barrier
	v_add_co_u32_e32 v200, vcc, s0, v118
	s_mov_b32 s0, 0x70000
	s_nop 0
	v_addc_co_u32_e32 v201, vcc, 0, v119, vcc
	v_add_co_u32_e32 v118, vcc, s0, v118
	global_load_dwordx4 v[200:203], v[200:201], off
	s_nop 0
	v_addc_co_u32_e32 v119, vcc, 0, v119, vcc
	global_load_dwordx4 v[196:199], v[118:119], off
	ds_read_b128 v[122:125], v211 offset:8192
	ds_read_b128 v[192:195], v211 offset:9216
	s_waitcnt lgkmcnt(1)
	v_mfma_f32_32x32x16_bf16 v[98:113], v[122:125], v[114:117], 0
	ds_read_b128 v[122:125], v211 offset:10240
	s_waitcnt lgkmcnt(1)
	v_mfma_f32_32x32x16_bf16 v[98:113], v[192:195], v[188:191], v[98:113]
	ds_read_b128 v[192:195], v211 offset:11264
	s_waitcnt lgkmcnt(1)
	v_mfma_f32_32x32x16_bf16 v[98:113], v[122:125], v[184:187], v[98:113]
	ds_read_b128 v[122:125], v211 offset:12288
	s_waitcnt lgkmcnt(1)
	v_mfma_f32_32x32x16_bf16 v[98:113], v[192:195], v[180:183], v[98:113]
	ds_read_b128 v[192:195], v211 offset:13312
	s_waitcnt lgkmcnt(1)
	v_mfma_f32_32x32x16_bf16 v[98:113], v[122:125], v[176:179], v[98:113]
	ds_read_b128 v[122:125], v211 offset:14336
	s_waitcnt lgkmcnt(1)
	v_mfma_f32_32x32x16_bf16 v[98:113], v[192:195], v[172:175], v[98:113]
	ds_read_b128 v[192:195], v211 offset:15360
	s_waitcnt lgkmcnt(1)
	v_mfma_f32_32x32x16_bf16 v[98:113], v[122:125], v[168:171], v[98:113]
	ds_read_b128 v[122:125], v211 offset:16384
	s_waitcnt lgkmcnt(1)
	v_mfma_f32_32x32x16_bf16 v[98:113], v[192:195], v[164:167], v[98:113]
	ds_read_b128 v[192:195], v211 offset:17408
	s_waitcnt lgkmcnt(1)
	v_mfma_f32_32x32x16_bf16 v[98:113], v[122:125], v[160:163], v[98:113]
	ds_read_b128 v[122:125], v211 offset:18432
	s_waitcnt lgkmcnt(1)
	v_mfma_f32_32x32x16_bf16 v[98:113], v[192:195], v[156:159], v[98:113]
	ds_read_b128 v[192:195], v211 offset:19456
	s_waitcnt lgkmcnt(1)
	v_mfma_f32_32x32x16_bf16 v[98:113], v[122:125], v[152:155], v[98:113]
	ds_read_b128 v[122:125], v211 offset:20480
	s_waitcnt lgkmcnt(1)
	v_mfma_f32_32x32x16_bf16 v[98:113], v[192:195], v[148:151], v[98:113]
	ds_read_b128 v[192:195], v211 offset:21504
	s_waitcnt lgkmcnt(1)
	v_mfma_f32_32x32x16_bf16 v[98:113], v[122:125], v[144:147], v[98:113]
	ds_read_b128 v[122:125], v211 offset:22528
	s_waitcnt lgkmcnt(1)
	v_mfma_f32_32x32x16_bf16 v[98:113], v[192:195], v[140:143], v[98:113]
	ds_read_b128 v[192:195], v211 offset:23552
	s_waitcnt lgkmcnt(1)
	v_mfma_f32_32x32x16_bf16 v[98:113], v[122:125], v[136:139], v[98:113]
	s_waitcnt lgkmcnt(0)
	v_mfma_f32_32x32x16_bf16 v[98:113], v[192:195], v[132:135], v[98:113]
	s_waitcnt vmcnt(0)
	ds_write_b128 v120, v[196:199] offset:24576
	ds_write_b128 v120, v[200:203] offset:24832
	s_waitcnt lgkmcnt(0)
	s_barrier
; #define LAS __attribute__((address_space(3)))
; __device__ __forceinline__ void attn_wg_unit(const Args& args, int l, int u, LAS unsigned char* lds, int tid_in) {
;     ...
; #pragma unroll
;     for (int kt = 0; kt < 8; ++kt) {
;         if (kt < 7) { s0 = *(const u32x4*)(ksrc + (size_t)(32 * (kt + 1)) * MW); s1 = *(const u32x4*)(ksrc + (size_t)(32 * (kt + 1) + 16) * MW); }
;         else { s0 = *(const u32x4*)(vsrc); s1 = *(const u32x4*)(vsrc + 8); }
;         const LAS unsigned char* cb = buf + (kt & 1) * 16384 + lane * 16;
;         f32x16 acc;
; #pragma unroll
;         for (int i = 0; i < 16; ++i) acc[i] = 0.f;
; #pragma unroll
;         for (int ks = 0; ks < 16; ++ks) { const bf16x8 kf = *(const LAS bf16x8*)(cb + ks * 1024); acc = __builtin_amdgcn_mfma_f32_32x32x16_bf16(kf, qf[ks], acc, 0, 0, 0); }
;         st[kt] = acc;
;         LAS unsigned char* nb = buf + ((kt + 1) & 1) * 16384;
;         if (kt < 7) { *(LAS u32x4*)(nb + kdst) = s0; *(LAS u32x4*)(nb + kdst + 256) = s1; }
;         else { *(LAS u32x4*)(nb + vdst) = (u32x4){s0.x, s0.y, s1.x, s1.y}; *(LAS u32x4*)(nb + vdst + 512) = (u32x4){s0.z, s0.w, s1.z, s1.w}; }
;         __syncthreads();
;     }
;     float mx = st[0][0];
; #pragma unroll
;     for (int kt = 0; kt < 8; ++kt)
; #pragma unroll
;         for (int i = 0; i < 16; ++i) mx = fmaxf(mx, st[kt][i]);
;     mx = fmaxf(mx, __shfl_xor(mx, 32));
	ds_read_b128 v[118:121], v211 offset:24576
	ds_read_b128 v[194:197], v211 offset:25600
	ds_read_b128 v[198:201], v211 offset:26624
	s_waitcnt lgkmcnt(2)
	v_mfma_f32_32x32x16_bf16 v[114:129], v[118:121], v[114:117], 0
	s_waitcnt lgkmcnt(1)
	v_mfma_f32_32x32x16_bf16 v[114:129], v[194:197], v[188:191], v[114:129]
	ds_read_b128 v[194:197], v211 offset:27648
	ds_read_b128 v[188:191], v211 offset:28672
	s_waitcnt lgkmcnt(2)
	v_mfma_f32_32x32x16_bf16 v[114:129], v[198:201], v[184:187], v[114:129]
	ds_read_b128 v[198:201], v211 offset:29696
	ds_read_b128 v[184:187], v211 offset:30720
	s_waitcnt lgkmcnt(3)
	v_mfma_f32_32x32x16_bf16 v[114:129], v[194:197], v[180:183], v[114:129]
	ds_read_b128 v[194:197], v211 offset:31744
	s_waitcnt lgkmcnt(3)
	v_mfma_f32_32x32x16_bf16 v[114:129], v[188:191], v[176:179], v[114:129]
	ds_read_b128 v[180:183], v211 offset:32768
	s_waitcnt lgkmcnt(3)
	v_mfma_f32_32x32x16_bf16 v[114:129], v[198:201], v[172:175], v[114:129]
	ds_read_b128 v[188:191], v211 offset:33792
	s_waitcnt lgkmcnt(3)
	v_mfma_f32_32x32x16_bf16 v[114:129], v[184:187], v[168:171], v[114:129]
	ds_read_b128 v[176:179], v211 offset:34816
	s_waitcnt lgkmcnt(3)
	v_mfma_f32_32x32x16_bf16 v[114:129], v[194:197], v[164:167], v[114:129]
	ds_read_b128 v[198:201], v211 offset:35840
	s_waitcnt lgkmcnt(3)
	v_mfma_f32_32x32x16_bf16 v[114:129], v[180:183], v[160:163], v[114:129]
	ds_read_b128 v[172:175], v211 offset:36864
	s_waitcnt lgkmcnt(3)
	v_mfma_f32_32x32x16_bf16 v[114:129], v[188:191], v[156:159], v[114:129]
	ds_read_b128 v[184:187], v211 offset:37888
	s_waitcnt lgkmcnt(3)
	v_mfma_f32_32x32x16_bf16 v[114:129], v[176:179], v[152:155], v[114:129]
	ds_read_b128 v[168:171], v211 offset:38912
	s_waitcnt lgkmcnt(3)
	v_mfma_f32_32x32x16_bf16 v[114:129], v[198:201], v[148:151], v[114:129]
	ds_read_b128 v[194:197], v211 offset:39936
	s_waitcnt lgkmcnt(3)
	v_mfma_f32_32x32x16_bf16 v[114:129], v[172:175], v[144:147], v[114:129]
	s_waitcnt lgkmcnt(2)
	v_mfma_f32_32x32x16_bf16 v[114:129], v[184:187], v[140:143], v[114:129]
	s_waitcnt lgkmcnt(1)
	v_mfma_f32_32x32x16_bf16 v[114:129], v[168:171], v[136:139], v[114:129]
	s_waitcnt lgkmcnt(0)
	v_mfma_f32_32x32x16_bf16 v[114:129], v[194:197], v[132:135], v[114:129]
	global_load_dwordx4 v[132:135], v[214:215], off offset:16
	global_load_dwordx4 v[136:139], v[214:215], off
	s_waitcnt vmcnt(1)
	v_mov_b32_e32 v142, v132
	v_mov_b32_e32 v143, v133
	s_waitcnt vmcnt(0)
	v_mov_b32_e32 v132, v138
	v_mov_b32_e32 v133, v139
	ds_write_b128 v216, v[132:135] offset:8704
	v_max_f32_e32 v132, v3, v3
	v_max_f32_e32 v133, v2, v2
	v_max_f32_e32 v132, v133, v132
	v_max3_f32 v132, v132, v4, v5
	v_max3_f32 v132, v132, v6, v7
	v_max3_f32 v132, v132, v8, v9
	v_max3_f32 v132, v132, v10, v11
	v_max3_f32 v132, v132, v12, v13
	v_max3_f32 v132, v132, v14, v15
	v_max3_f32 v132, v132, v16, v17
	v_max3_f32 v132, v132, v18, v19
	v_max3_f32 v132, v132, v20, v21
	v_max3_f32 v132, v132, v22, v23
	v_max3_f32 v132, v132, v24, v25
	v_max3_f32 v132, v132, v26, v27
	v_max3_f32 v132, v132, v28, v29
	v_max3_f32 v132, v132, v30, v31
	v_max3_f32 v132, v132, v32, v33
	v_max3_f32 v132, v132, v34, v35
	v_max3_f32 v132, v132, v36, v37
	v_max3_f32 v132, v132, v38, v39
	v_max3_f32 v132, v132, v40, v41
	v_max3_f32 v132, v132, v42, v43
	v_max3_f32 v132, v132, v44, v45
	v_max3_f32 v132, v132, v46, v47
	v_max3_f32 v132, v132, v48, v49
	v_max3_f32 v132, v132, v50, v51
	v_max3_f32 v132, v132, v52, v53
	v_max3_f32 v132, v132, v54, v55
	v_max3_f32 v132, v132, v56, v57
	v_max3_f32 v132, v132, v58, v59
	v_max3_f32 v132, v132, v60, v61
	v_max3_f32 v132, v132, v62, v63
	v_max3_f32 v132, v132, v64, v65
	v_max3_f32 v132, v132, v66, v67
	v_max3_f32 v132, v132, v68, v69
	v_max3_f32 v132, v132, v70, v71
	v_max3_f32 v132, v132, v72, v73
	v_max3_f32 v132, v132, v74, v75
	v_max3_f32 v132, v132, v76, v77
	v_max3_f32 v132, v132, v78, v79
	v_max3_f32 v132, v132, v80, v81
	v_max3_f32 v132, v132, v82, v83
	v_max3_f32 v132, v132, v84, v85
	v_max3_f32 v132, v132, v86, v87
	v_max3_f32 v132, v132, v88, v89
	v_max3_f32 v132, v132, v90, v91
	v_max3_f32 v132, v132, v92, v93
	v_max3_f32 v132, v132, v94, v95
	v_max3_f32 v132, v132, v96, v97
	v_max3_f32 v132, v132, v98, v99
	v_max3_f32 v132, v132, v100, v101
	v_max3_f32 v132, v132, v102, v103
	v_max3_f32 v132, v132, v104, v105
	v_max3_f32 v132, v132, v106, v107
	v_max3_f32 v132, v132, v108, v109
	v_max3_f32 v132, v132, v110, v111
	v_max3_f32 v132, v132, v112, v113
	v_max3_f32 v132, v132, v114, v115
	v_max3_f32 v132, v132, v116, v117
	v_max3_f32 v132, v132, v118, v119
	v_max3_f32 v132, v132, v120, v121
	v_and_b32_e32 v134, 64, v204
	v_max3_f32 v132, v132, v122, v123
	v_xor_b32_e32 v133, 32, v204
	v_add_u32_e32 v134, 64, v134
	v_max3_f32 v132, v132, v124, v125
	v_cmp_lt_i32_e32 vcc, v133, v134
	v_max3_f32 v132, v132, v126, v127
	v_max3_f32 v132, v132, v128, v129
	v_cndmask_b32_e32 v133, v204, v133, vcc
	v_lshlrev_b32_e32 v196, 2, v133
	ds_bpermute_b32 v133, v196, v132
	v_mov_b32_e32 v140, v136
	v_mov_b32_e32 v141, v137
	ds_write_b128 v216, v[140:143] offset:8192
	s_waitcnt lgkmcnt(0)
; __device__ __forceinline__ unsigned cvtpk(float lo, float hi) { f32x2 v = {lo, hi}; bf16x2_t b = __builtin_convertvector(v, bf16x2_t); return __builtin_bit_cast(unsigned, b); }
; __device__ __forceinline__ void attn_wg_unit(const Args& args, int l, int u, LAS unsigned char* lds, int tid_in) {
;     ...
;     float sum = 0.f;
;     bf16x8 pf[8][2];
; #pragma unroll
;     for (int kt = 0; kt < 8; ++kt) {
; #pragma unroll
;         for (int i = 0; i < 16; ++i) { const float e = __builtin_amdgcn_exp2f(st[kt][i] - mx); st[kt][i] = e; sum += e; }
; #pragma unroll
;         for (int s = 0; s < 2; ++s) { u32x4 w; w.x = cvtpk(st[kt][8 * s + 0], st[kt][8 * s + 1]); w.y = cvtpk(st[kt][8 * s + 2], st[kt][8 * s + 3]); w.z = cvtpk(st[kt][8 * s + 4], st[kt][8 * s + 5]); w.w = cvtpk(st[kt][8 * s + 6], st[kt][8 * s + 7]);
;             pf[kt][s] = __builtin_bit_cast(bf16x8, w); }
;     }
	v_max_f32_e32 v133, v133, v133
	v_max_f32_e32 v140, v132, v133
	v_sub_f32_e32 v2, v2, v140
	v_sub_f32_e32 v3, v3, v140
	v_exp_f32_e32 v2, v2
	v_exp_f32_e32 v3, v3
	v_sub_f32_e32 v4, v4, v140
	v_exp_f32_e32 v4, v4
	v_sub_f32_e32 v5, v5, v140
	v_exp_f32_e32 v5, v5
	v_sub_f32_e32 v6, v6, v140
	v_exp_f32_e32 v6, v6
	v_sub_f32_e32 v7, v7, v140
	v_cvt_pk_bf16_f32 v192, v2, v3
	v_add_f32_e32 v2, 0, v2
	v_exp_f32_e32 v7, v7
	v_sub_f32_e32 v8, v8, v140
	v_add_f32_e32 v2, v3, v2
	v_exp_f32_e32 v8, v8
	v_sub_f32_e32 v9, v9, v140
	v_add_f32_e32 v2, v4, v2
	v_exp_f32_e32 v9, v9
	v_sub_f32_e32 v10, v10, v140
	v_add_f32_e32 v2, v5, v2
	v_exp_f32_e32 v10, v10
	v_sub_f32_e32 v11, v11, v140
	v_add_f32_e32 v2, v6, v2
	v_exp_f32_e32 v11, v11
	v_sub_f32_e32 v12, v12, v140
	v_add_f32_e32 v2, v7, v2
	v_exp_f32_e32 v12, v12
	v_sub_f32_e32 v13, v13, v140
	v_add_f32_e32 v2, v8, v2
	v_exp_f32_e32 v13, v13
	v_sub_f32_e32 v14, v14, v140
	v_add_f32_e32 v2, v9, v2
	v_exp_f32_e32 v14, v14
	v_sub_f32_e32 v15, v15, v140
	v_add_f32_e32 v2, v10, v2
	v_exp_f32_e32 v15, v15
	v_sub_f32_e32 v16, v16, v140
	v_add_f32_e32 v2, v11, v2
	v_exp_f32_e32 v16, v16
	v_sub_f32_e32 v17, v17, v140
	v_add_f32_e32 v2, v12, v2
	v_exp_f32_e32 v17, v17
	v_add_f32_e32 v2, v13, v2
	v_sub_f32_e32 v3, v18, v140
	v_cvt_pk_bf16_f32 v193, v4, v5
	v_add_f32_e32 v2, v14, v2
	v_exp_f32_e32 v3, v3
	v_sub_f32_e32 v4, v19, v140
	v_add_f32_e32 v2, v15, v2
	v_exp_f32_e32 v4, v4
	v_sub_f32_e32 v5, v20, v140
	v_cvt_pk_bf16_f32 v194, v6, v7
	v_add_f32_e32 v2, v16, v2
	v_exp_f32_e32 v5, v5
	v_sub_f32_e32 v6, v21, v140
	v_add_f32_e32 v2, v17, v2
	v_exp_f32_e32 v6, v6
	v_sub_f32_e32 v7, v22, v140
	v_cvt_pk_bf16_f32 v195, v8, v9
	v_exp_f32_e32 v7, v7
	v_sub_f32_e32 v8, v23, v140
	v_add_f32_e32 v2, v3, v2
	v_exp_f32_e32 v8, v8
	v_sub_f32_e32 v9, v24, v140
	v_add_f32_e32 v2, v4, v2
	v_cvt_pk_bf16_f32 v188, v10, v11
	v_exp_f32_e32 v9, v9
	v_sub_f32_e32 v10, v25, v140
	v_add_f32_e32 v2, v5, v2
	v_exp_f32_e32 v10, v10
	v_sub_f32_e32 v11, v26, v140
	v_add_f32_e32 v2, v6, v2
	v_cvt_pk_bf16_f32 v189, v12, v13
	v_exp_f32_e32 v11, v11
	v_sub_f32_e32 v12, v27, v140
	v_add_f32_e32 v2, v7, v2
	v_exp_f32_e32 v12, v12
	v_sub_f32_e32 v13, v28, v140
	v_add_f32_e32 v2, v8, v2
	v_cvt_pk_bf16_f32 v190, v14, v15
	v_exp_f32_e32 v13, v13
	v_sub_f32_e32 v14, v29, v140
	v_add_f32_e32 v2, v9, v2
	v_exp_f32_e32 v14, v14
	v_sub_f32_e32 v15, v30, v140
	v_add_f32_e32 v2, v10, v2
	v_cvt_pk_bf16_f32 v191, v16, v17
	v_exp_f32_e32 v15, v15
	v_sub_f32_e32 v16, v31, v140
	v_add_f32_e32 v2, v11, v2
	v_exp_f32_e32 v16, v16
	v_sub_f32_e32 v17, v32, v140
	v_add_f32_e32 v2, v12, v2
	v_exp_f32_e32 v17, v17
	v_sub_f32_e32 v18, v33, v140
	v_add_f32_e32 v2, v13, v2
	v_exp_f32_e32 v18, v18
	v_cvt_pk_bf16_f32 v184, v3, v4
	v_add_f32_e32 v2, v14, v2
	v_sub_f32_e32 v3, v34, v140
	v_add_f32_e32 v2, v15, v2
	v_exp_f32_e32 v3, v3
	v_sub_f32_e32 v4, v35, v140
	v_cvt_pk_bf16_f32 v185, v5, v6
	v_add_f32_e32 v2, v16, v2
	v_exp_f32_e32 v4, v4
	v_sub_f32_e32 v5, v36, v140
	v_add_f32_e32 v2, v17, v2
	v_exp_f32_e32 v5, v5
	v_sub_f32_e32 v6, v37, v140
	v_cvt_pk_bf16_f32 v186, v7, v8
	v_add_f32_e32 v2, v18, v2
	v_exp_f32_e32 v6, v6
	v_sub_f32_e32 v7, v38, v140
	v_exp_f32_e32 v7, v7
	v_sub_f32_e32 v8, v39, v140
	v_add_f32_e32 v2, v3, v2
	v_cvt_pk_bf16_f32 v187, v9, v10
	v_exp_f32_e32 v8, v8
	v_sub_f32_e32 v9, v40, v140
	v_add_f32_e32 v2, v4, v2
	v_exp_f32_e32 v9, v9
	v_sub_f32_e32 v10, v41, v140
	v_add_f32_e32 v2, v5, v2
	v_cvt_pk_bf16_f32 v180, v11, v12
	v_exp_f32_e32 v10, v10
	v_sub_f32_e32 v11, v42, v140
	v_add_f32_e32 v2, v6, v2
	v_exp_f32_e32 v11, v11
	v_sub_f32_e32 v12, v43, v140
	v_add_f32_e32 v2, v7, v2
	v_cvt_pk_bf16_f32 v181, v13, v14
	v_exp_f32_e32 v12, v12
	v_sub_f32_e32 v13, v44, v140
	v_add_f32_e32 v2, v8, v2
	v_exp_f32_e32 v13, v13
	v_sub_f32_e32 v14, v45, v140
	v_add_f32_e32 v2, v9, v2
	v_cvt_pk_bf16_f32 v182, v15, v16
	v_exp_f32_e32 v14, v14
	v_sub_f32_e32 v15, v46, v140
	v_add_f32_e32 v2, v10, v2
	v_exp_f32_e32 v15, v15
	v_sub_f32_e32 v16, v47, v140
	v_add_f32_e32 v2, v11, v2
	v_cvt_pk_bf16_f32 v183, v17, v18
	v_exp_f32_e32 v16, v16
	v_sub_f32_e32 v17, v48, v140
	v_add_f32_e32 v2, v12, v2
	v_exp_f32_e32 v17, v17
	v_sub_f32_e32 v18, v49, v140
	v_add_f32_e32 v2, v13, v2
	v_exp_f32_e32 v18, v18
	v_cvt_pk_bf16_f32 v176, v3, v4
	v_add_f32_e32 v2, v14, v2
	v_sub_f32_e32 v3, v50, v140
	v_add_f32_e32 v2, v15, v2
	v_exp_f32_e32 v3, v3
	v_sub_f32_e32 v4, v51, v140
	v_cvt_pk_bf16_f32 v177, v5, v6
	v_add_f32_e32 v2, v16, v2
	v_exp_f32_e32 v4, v4
	v_sub_f32_e32 v5, v52, v140
	v_add_f32_e32 v2, v17, v2
	v_exp_f32_e32 v5, v5
	v_sub_f32_e32 v6, v53, v140
	v_cvt_pk_bf16_f32 v178, v7, v8
	v_add_f32_e32 v2, v18, v2
	v_exp_f32_e32 v6, v6
	v_sub_f32_e32 v7, v54, v140
	v_exp_f32_e32 v7, v7
	v_sub_f32_e32 v8, v55, v140
	v_add_f32_e32 v2, v3, v2
	v_cvt_pk_bf16_f32 v179, v9, v10
	v_exp_f32_e32 v8, v8
	v_sub_f32_e32 v9, v56, v140
	v_add_f32_e32 v2, v4, v2
	v_exp_f32_e32 v9, v9
	v_sub_f32_e32 v10, v57, v140
	v_add_f32_e32 v2, v5, v2
	v_cvt_pk_bf16_f32 v172, v11, v12
	v_exp_f32_e32 v10, v10
	v_sub_f32_e32 v11, v58, v140
	v_add_f32_e32 v2, v6, v2
	v_exp_f32_e32 v11, v11
	v_sub_f32_e32 v12, v59, v140
	v_add_f32_e32 v2, v7, v2
	v_cvt_pk_bf16_f32 v173, v13, v14
	v_exp_f32_e32 v12, v12
	v_sub_f32_e32 v13, v60, v140
	v_add_f32_e32 v2, v8, v2
	v_exp_f32_e32 v13, v13
	v_sub_f32_e32 v14, v61, v140
	v_add_f32_e32 v2, v9, v2
	v_cvt_pk_bf16_f32 v174, v15, v16
	v_exp_f32_e32 v14, v14
	v_sub_f32_e32 v15, v62, v140
	v_add_f32_e32 v2, v10, v2
	v_exp_f32_e32 v15, v15
	v_sub_f32_e32 v16, v63, v140
	v_add_f32_e32 v2, v11, v2
	v_cvt_pk_bf16_f32 v175, v17, v18
	v_exp_f32_e32 v16, v16
	v_sub_f32_e32 v17, v64, v140
; __device__ __forceinline__ unsigned cvtpk(float lo, float hi) { f32x2 v = {lo, hi}; bf16x2_t b = __builtin_convertvector(v, bf16x2_t); return __builtin_bit_cast(unsigned, b); }
; __device__ __forceinline__ void attn_wg_unit(const Args& args, int l, int u, LAS unsigned char* lds, int tid_in) {
;     ...
;     float sum = 0.f;
;     bf16x8 pf[8][2];
; #pragma unroll
;     for (int kt = 0; kt < 8; ++kt) {
; #pragma unroll
;         for (int i = 0; i < 16; ++i) { const float e = __builtin_amdgcn_exp2f(st[kt][i] - mx); st[kt][i] = e; sum += e; }
; #pragma unroll
;         for (int s = 0; s < 2; ++s) { u32x4 w; w.x = cvtpk(st[kt][8 * s + 0], st[kt][8 * s + 1]); w.y = cvtpk(st[kt][8 * s + 2], st[kt][8 * s + 3]); w.z = cvtpk(st[kt][8 * s + 4], st[kt][8 * s + 5]); w.w = cvtpk(st[kt][8 * s + 6], st[kt][8 * s + 7]);
;             pf[kt][s] = __builtin_bit_cast(bf16x8, w); }
;     }
;     sum += __shfl_xor(sum, 32);
	v_add_f32_e32 v2, v12, v2
	v_exp_f32_e32 v17, v17
	v_sub_f32_e32 v18, v65, v140
	v_add_f32_e32 v2, v13, v2
	v_exp_f32_e32 v18, v18
	v_cvt_pk_bf16_f32 v168, v3, v4
	v_add_f32_e32 v2, v14, v2
	v_sub_f32_e32 v3, v66, v140
	v_add_f32_e32 v2, v15, v2
	v_exp_f32_e32 v3, v3
	v_sub_f32_e32 v4, v67, v140
	v_cvt_pk_bf16_f32 v169, v5, v6
	v_add_f32_e32 v2, v16, v2
	v_exp_f32_e32 v4, v4
	v_sub_f32_e32 v5, v68, v140
	v_add_f32_e32 v2, v17, v2
	v_exp_f32_e32 v5, v5
	v_sub_f32_e32 v6, v69, v140
	v_cvt_pk_bf16_f32 v170, v7, v8
	v_add_f32_e32 v2, v18, v2
	v_exp_f32_e32 v6, v6
	v_sub_f32_e32 v7, v70, v140
	v_exp_f32_e32 v7, v7
	v_sub_f32_e32 v8, v71, v140
	v_add_f32_e32 v2, v3, v2
	v_cvt_pk_bf16_f32 v171, v9, v10
	v_exp_f32_e32 v8, v8
	v_sub_f32_e32 v9, v72, v140
	v_add_f32_e32 v2, v4, v2
	v_exp_f32_e32 v9, v9
	v_sub_f32_e32 v10, v73, v140
	v_add_f32_e32 v2, v5, v2
	v_cvt_pk_bf16_f32 v164, v11, v12
	v_exp_f32_e32 v10, v10
	v_sub_f32_e32 v11, v74, v140
	v_add_f32_e32 v2, v6, v2
	v_exp_f32_e32 v11, v11
	v_sub_f32_e32 v12, v75, v140
	v_add_f32_e32 v2, v7, v2
	v_cvt_pk_bf16_f32 v165, v13, v14
	v_exp_f32_e32 v12, v12
	v_sub_f32_e32 v13, v76, v140
	v_add_f32_e32 v2, v8, v2
	v_exp_f32_e32 v13, v13
	v_sub_f32_e32 v14, v77, v140
	v_add_f32_e32 v2, v9, v2
	v_cvt_pk_bf16_f32 v166, v15, v16
	v_exp_f32_e32 v14, v14
	v_sub_f32_e32 v15, v78, v140
	v_add_f32_e32 v2, v10, v2
	v_exp_f32_e32 v15, v15
	v_sub_f32_e32 v16, v79, v140
	v_add_f32_e32 v2, v11, v2
	v_cvt_pk_bf16_f32 v167, v17, v18
	v_exp_f32_e32 v16, v16
	v_sub_f32_e32 v17, v80, v140
	v_add_f32_e32 v2, v12, v2
	v_exp_f32_e32 v17, v17
	v_sub_f32_e32 v18, v81, v140
	v_add_f32_e32 v2, v13, v2
	v_exp_f32_e32 v18, v18
	v_cvt_pk_bf16_f32 v160, v3, v4
	v_add_f32_e32 v2, v14, v2
	v_sub_f32_e32 v3, v82, v140
	v_add_f32_e32 v2, v15, v2
	v_exp_f32_e32 v3, v3
	v_sub_f32_e32 v4, v83, v140
	v_cvt_pk_bf16_f32 v161, v5, v6
	v_add_f32_e32 v2, v16, v2
	v_exp_f32_e32 v4, v4
	v_sub_f32_e32 v5, v84, v140
	v_add_f32_e32 v2, v17, v2
	v_exp_f32_e32 v5, v5
	v_sub_f32_e32 v6, v85, v140
	v_cvt_pk_bf16_f32 v162, v7, v8
	v_add_f32_e32 v2, v18, v2
	v_exp_f32_e32 v6, v6
	v_sub_f32_e32 v7, v86, v140
	v_exp_f32_e32 v7, v7
	v_sub_f32_e32 v8, v87, v140
	v_add_f32_e32 v2, v3, v2
	v_cvt_pk_bf16_f32 v163, v9, v10
	v_exp_f32_e32 v8, v8
	v_sub_f32_e32 v9, v88, v140
	v_add_f32_e32 v2, v4, v2
	v_exp_f32_e32 v9, v9
	v_sub_f32_e32 v10, v89, v140
	v_add_f32_e32 v2, v5, v2
	v_cvt_pk_bf16_f32 v156, v11, v12
	v_exp_f32_e32 v10, v10
	v_sub_f32_e32 v11, v90, v140
	v_add_f32_e32 v2, v6, v2
	v_exp_f32_e32 v11, v11
	v_sub_f32_e32 v12, v91, v140
	v_add_f32_e32 v2, v7, v2
	v_cvt_pk_bf16_f32 v157, v13, v14
	v_exp_f32_e32 v12, v12
	v_sub_f32_e32 v13, v92, v140
	v_add_f32_e32 v2, v8, v2
	v_exp_f32_e32 v13, v13
	v_sub_f32_e32 v14, v93, v140
	v_add_f32_e32 v2, v9, v2
	v_cvt_pk_bf16_f32 v158, v15, v16
	v_exp_f32_e32 v14, v14
	v_sub_f32_e32 v15, v94, v140
	v_add_f32_e32 v2, v10, v2
	v_exp_f32_e32 v15, v15
	v_sub_f32_e32 v16, v95, v140
	v_add_f32_e32 v2, v11, v2
	v_cvt_pk_bf16_f32 v159, v17, v18
	v_exp_f32_e32 v16, v16
	v_sub_f32_e32 v17, v96, v140
	v_add_f32_e32 v2, v12, v2
	v_exp_f32_e32 v17, v17
	v_sub_f32_e32 v18, v97, v140
	v_add_f32_e32 v2, v13, v2
	v_exp_f32_e32 v18, v18
	v_cvt_pk_bf16_f32 v152, v3, v4
	v_add_f32_e32 v2, v14, v2
	v_sub_f32_e32 v3, v98, v140
	v_add_f32_e32 v2, v15, v2
	v_exp_f32_e32 v3, v3
	v_sub_f32_e32 v4, v99, v140
	v_cvt_pk_bf16_f32 v153, v5, v6
	v_add_f32_e32 v2, v16, v2
	v_exp_f32_e32 v4, v4
	v_sub_f32_e32 v5, v100, v140
	v_add_f32_e32 v2, v17, v2
	v_exp_f32_e32 v5, v5
	v_sub_f32_e32 v6, v101, v140
	v_cvt_pk_bf16_f32 v154, v7, v8
	v_add_f32_e32 v2, v18, v2
	v_exp_f32_e32 v6, v6
	v_sub_f32_e32 v7, v102, v140
	v_exp_f32_e32 v7, v7
	v_sub_f32_e32 v8, v103, v140
	v_add_f32_e32 v2, v3, v2
	v_cvt_pk_bf16_f32 v155, v9, v10
	v_exp_f32_e32 v8, v8
	v_sub_f32_e32 v9, v104, v140
	v_add_f32_e32 v2, v4, v2
	v_exp_f32_e32 v9, v9
	v_sub_f32_e32 v10, v105, v140
	v_add_f32_e32 v2, v5, v2
	v_cvt_pk_bf16_f32 v148, v11, v12
	v_exp_f32_e32 v10, v10
	v_sub_f32_e32 v11, v106, v140
	v_add_f32_e32 v2, v6, v2
	v_exp_f32_e32 v11, v11
	v_sub_f32_e32 v12, v107, v140
	v_add_f32_e32 v2, v7, v2
	v_cvt_pk_bf16_f32 v149, v13, v14
	v_exp_f32_e32 v12, v12
	v_sub_f32_e32 v13, v108, v140
	v_add_f32_e32 v2, v8, v2
	v_exp_f32_e32 v13, v13
	v_sub_f32_e32 v14, v109, v140
	v_add_f32_e32 v2, v9, v2
	v_cvt_pk_bf16_f32 v150, v15, v16
	v_exp_f32_e32 v14, v14
	v_sub_f32_e32 v15, v110, v140
	v_add_f32_e32 v2, v10, v2
	v_exp_f32_e32 v15, v15
	v_sub_f32_e32 v16, v111, v140
	v_add_f32_e32 v2, v11, v2
	v_cvt_pk_bf16_f32 v151, v17, v18
	v_exp_f32_e32 v16, v16
	v_sub_f32_e32 v17, v112, v140
	v_add_f32_e32 v2, v12, v2
	v_exp_f32_e32 v17, v17
	v_sub_f32_e32 v18, v113, v140
	v_add_f32_e32 v2, v13, v2
	v_exp_f32_e32 v18, v18
	v_cvt_pk_bf16_f32 v136, v3, v4
	v_add_f32_e32 v2, v14, v2
	v_sub_f32_e32 v3, v114, v140
	v_add_f32_e32 v2, v15, v2
	v_exp_f32_e32 v3, v3
	v_sub_f32_e32 v4, v115, v140
	v_cvt_pk_bf16_f32 v137, v5, v6
	v_add_f32_e32 v2, v16, v2
	v_exp_f32_e32 v4, v4
	v_sub_f32_e32 v5, v116, v140
	v_add_f32_e32 v2, v17, v2
	v_exp_f32_e32 v5, v5
	v_sub_f32_e32 v6, v117, v140
	v_cvt_pk_bf16_f32 v138, v7, v8
	v_add_f32_e32 v2, v18, v2
	v_exp_f32_e32 v6, v6
	v_sub_f32_e32 v7, v118, v140
	v_exp_f32_e32 v7, v7
	v_sub_f32_e32 v8, v119, v140
	v_add_f32_e32 v2, v3, v2
	v_cvt_pk_bf16_f32 v139, v9, v10
	v_exp_f32_e32 v8, v8
	v_sub_f32_e32 v9, v120, v140
	v_add_f32_e32 v2, v4, v2
	v_exp_f32_e32 v9, v9
	v_sub_f32_e32 v10, v121, v140
	v_add_f32_e32 v2, v5, v2
	v_cvt_pk_bf16_f32 v132, v11, v12
	v_exp_f32_e32 v10, v10
	v_sub_f32_e32 v11, v122, v140
	v_add_f32_e32 v2, v6, v2
	v_exp_f32_e32 v11, v11
	v_sub_f32_e32 v12, v123, v140
	v_add_f32_e32 v2, v7, v2
	v_cvt_pk_bf16_f32 v133, v13, v14
	v_exp_f32_e32 v12, v12
	v_sub_f32_e32 v13, v124, v140
	v_add_f32_e32 v2, v8, v2
	v_exp_f32_e32 v13, v13
	v_sub_f32_e32 v14, v125, v140
	v_add_f32_e32 v2, v9, v2
	v_cvt_pk_bf16_f32 v134, v15, v16
	v_exp_f32_e32 v14, v14
	v_sub_f32_e32 v15, v126, v140
	v_add_f32_e32 v2, v10, v2
	v_exp_f32_e32 v15, v15
	v_sub_f32_e32 v16, v127, v140
	v_add_f32_e32 v2, v11, v2
	v_cvt_pk_bf16_f32 v135, v17, v18
	v_exp_f32_e32 v16, v16
	v_sub_f32_e32 v17, v128, v140
	v_add_f32_e32 v2, v12, v2
	v_exp_f32_e32 v17, v17
	v_sub_f32_e32 v18, v129, v140
	v_add_f32_e32 v2, v13, v2
	v_exp_f32_e32 v18, v18
	v_add_f32_e32 v2, v14, v2
	v_add_f32_e32 v2, v15, v2
	v_add_f32_e32 v2, v16, v2
	v_add_f32_e32 v2, v17, v2
	v_add_f32_e32 v217, v18, v2
	s_barrier
; #define LAS __attribute__((address_space(3)))
; __device__ __forceinline__ void attn_wg_unit(const Args& args, int l, int u, LAS unsigned char* lds, int tid_in) {
;     ...
;     sum += __shfl_xor(sum, 32);
;     const float inv = __builtin_amdgcn_rcpf(sum);
;     f32x16 ot[8];
; #pragma unroll
;     for (int dt = 0; dt < 8; ++dt)
; #pragma unroll
;         for (int i = 0; i < 16; ++i) ot[dt][i] = 0.f;
; #pragma unroll
;     for (int kt = 0; kt < 8; ++kt) {
;         if (kt < 7) { s0 = *(const u32x4*)(vsrc + 32 * (kt + 1)); s1 = *(const u32x4*)(vsrc + 32 * (kt + 1) + 8); }
;         const LAS unsigned char* cb = buf + (kt & 1) * 16384 + lane * 16;
; #pragma unroll
;         for (int dt = 0; dt < 8; ++dt)
; #pragma unroll
;             for (int s = 0; s < 2; ++s) { const bf16x8 vf = *(const LAS bf16x8*)(cb + (dt * 2 + s) * 1024); ot[dt] = __builtin_amdgcn_mfma_f32_32x32x16_bf16(vf, pf[kt][s], ot[dt], 0, 0, 0); }
;         if (kt < 7) {
;             LAS unsigned char* nb = buf + ((kt + 1) & 1) * 16384;
;             *(LAS u32x4*)(nb + vdst) = (u32x4){s0.x, s0.y, s1.x, s1.y}; *(LAS u32x4*)(nb + vdst + 512) = (u32x4){s0.z, s0.w, s1.z, s1.w};
;         }
;         __syncthreads();
;     }
	v_cvt_pk_bf16_f32 v140, v3, v4
	v_cvt_pk_bf16_f32 v141, v5, v6
	ds_bpermute_b32 v218, v196, v217
	global_load_dwordx4 v[196:199], v[214:215], off offset:80
	global_load_dwordx4 v[200:203], v[214:215], off offset:64
	ds_read_b128 v[2:5], v211 offset:8192
	v_cvt_pk_bf16_f32 v147, v17, v18
	ds_read_b128 v[18:21], v211 offset:9216
	v_cvt_pk_bf16_f32 v142, v7, v8
	v_cvt_pk_bf16_f32 v143, v9, v10
	v_cvt_pk_bf16_f32 v144, v11, v12
	v_cvt_pk_bf16_f32 v145, v13, v14
	v_cvt_pk_bf16_f32 v146, v15, v16
	s_waitcnt lgkmcnt(1)
	v_mfma_f32_32x32x16_bf16 v[2:17], v[2:5], v[192:195], 0
	ds_read_b128 v[66:69], v211 offset:15360
	ds_read_b128 v[82:85], v211 offset:17408
	ds_read_b128 v[114:117], v211 offset:21504
	s_waitcnt lgkmcnt(3)
	v_mfma_f32_32x32x16_bf16 v[2:17], v[18:21], v[188:191], v[2:17]
	ds_read_b128 v[18:21], v211 offset:10240
	s_waitcnt lgkmcnt(0)
	v_mfma_f32_32x32x16_bf16 v[50:65], v[18:21], v[192:195], 0
	ds_read_b128 v[18:21], v211 offset:11264
	s_waitcnt lgkmcnt(0)
	v_mfma_f32_32x32x16_bf16 v[50:65], v[18:21], v[188:191], v[50:65]
	ds_read_b128 v[18:21], v211 offset:12288
	s_waitcnt lgkmcnt(0)
	v_mfma_f32_32x32x16_bf16 v[34:49], v[18:21], v[192:195], 0
	ds_read_b128 v[18:21], v211 offset:13312
	s_waitcnt lgkmcnt(0)
	v_mfma_f32_32x32x16_bf16 v[34:49], v[18:21], v[188:191], v[34:49]
	ds_read_b128 v[18:21], v211 offset:14336
	s_waitcnt lgkmcnt(0)
	v_mfma_f32_32x32x16_bf16 v[18:33], v[18:21], v[192:195], 0
	v_mfma_f32_32x32x16_bf16 v[18:33], v[66:69], v[188:191], v[18:33]
	ds_read_b128 v[66:69], v211 offset:16384
	s_waitcnt lgkmcnt(0)
	v_mfma_f32_32x32x16_bf16 v[66:81], v[66:69], v[192:195], 0
	v_mfma_f32_32x32x16_bf16 v[66:81], v[82:85], v[188:191], v[66:81]
	ds_read_b128 v[82:85], v211 offset:18432
	s_waitcnt lgkmcnt(0)
	v_mfma_f32_32x32x16_bf16 v[98:113], v[82:85], v[192:195], 0
	ds_read_b128 v[82:85], v211 offset:19456
	s_waitcnt lgkmcnt(0)
	v_mfma_f32_32x32x16_bf16 v[98:113], v[82:85], v[188:191], v[98:113]
	ds_read_b128 v[82:85], v211 offset:20480
	s_waitcnt lgkmcnt(0)
	v_mfma_f32_32x32x16_bf16 v[82:97], v[82:85], v[192:195], 0
	v_mfma_f32_32x32x16_bf16 v[82:97], v[114:117], v[188:191], v[82:97]
	ds_read_b128 v[114:117], v211 offset:22528
	s_waitcnt lgkmcnt(0)
	v_mfma_f32_32x32x16_bf16 v[114:129], v[114:117], v[192:195], 0
	ds_read_b128 v[192:195], v211 offset:23552
	s_waitcnt lgkmcnt(0)
	v_mfma_f32_32x32x16_bf16 v[114:129], v[192:195], v[188:191], v[114:129]
	s_waitcnt vmcnt(0)
	v_mov_b32_e32 v188, v202
	v_mov_b32_e32 v189, v203
	v_mov_b32_e32 v190, v198
	v_mov_b32_e32 v191, v199
	v_mov_b32_e32 v202, v196
	v_mov_b32_e32 v203, v197
	ds_write_b128 v216, v[200:203] offset:24576
	ds_write_b128 v216, v[188:191] offset:25088
	s_waitcnt lgkmcnt(0)
	s_barrier
	global_load_dwordx4 v[188:191], v[214:215], off offset:144
	global_load_dwordx4 v[192:195], v[214:215], off offset:128
	ds_read_b128 v[196:199], v211 offset:24576
	ds_read_b128 v[200:203], v211 offset:25600
	s_waitcnt lgkmcnt(1)
	v_mfma_f32_32x32x16_bf16 v[2:17], v[196:199], v[184:187], v[2:17]
	ds_read_b128 v[196:199], v211 offset:26624
	s_waitcnt lgkmcnt(1)
	v_mfma_f32_32x32x16_bf16 v[2:17], v[200:203], v[180:183], v[2:17]
	ds_read_b128 v[200:203], v211 offset:27648
	s_waitcnt lgkmcnt(1)
	v_mfma_f32_32x32x16_bf16 v[50:65], v[196:199], v[184:187], v[50:65]
	ds_read_b128 v[196:199], v211 offset:28672
	s_waitcnt lgkmcnt(1)
	v_mfma_f32_32x32x16_bf16 v[50:65], v[200:203], v[180:183], v[50:65]
	ds_read_b128 v[200:203], v211 offset:29696
	s_waitcnt lgkmcnt(1)
	v_mfma_f32_32x32x16_bf16 v[34:49], v[196:199], v[184:187], v[34:49]
	ds_read_b128 v[196:199], v211 offset:30720
	s_waitcnt lgkmcnt(1)
	v_mfma_f32_32x32x16_bf16 v[34:49], v[200:203], v[180:183], v[34:49]
	ds_read_b128 v[200:203], v211 offset:31744
	s_waitcnt lgkmcnt(1)
	v_mfma_f32_32x32x16_bf16 v[18:33], v[196:199], v[184:187], v[18:33]
	ds_read_b128 v[196:199], v211 offset:32768
	s_waitcnt lgkmcnt(1)
	v_mfma_f32_32x32x16_bf16 v[18:33], v[200:203], v[180:183], v[18:33]
	ds_read_b128 v[200:203], v211 offset:33792
	s_waitcnt lgkmcnt(1)
	v_mfma_f32_32x32x16_bf16 v[66:81], v[196:199], v[184:187], v[66:81]
	ds_read_b128 v[196:199], v211 offset:34816
	s_waitcnt lgkmcnt(1)
	v_mfma_f32_32x32x16_bf16 v[66:81], v[200:203], v[180:183], v[66:81]
	ds_read_b128 v[200:203], v211 offset:35840
	s_waitcnt lgkmcnt(1)
	v_mfma_f32_32x32x16_bf16 v[98:113], v[196:199], v[184:187], v[98:113]
	ds_read_b128 v[196:199], v211 offset:36864
	s_waitcnt lgkmcnt(1)
	v_mfma_f32_32x32x16_bf16 v[98:113], v[200:203], v[180:183], v[98:113]
	ds_read_b128 v[200:203], v211 offset:37888
	s_waitcnt lgkmcnt(1)
	v_mfma_f32_32x32x16_bf16 v[82:97], v[196:199], v[184:187], v[82:97]
	ds_read_b128 v[196:199], v211 offset:38912
	s_waitcnt lgkmcnt(1)
	v_mfma_f32_32x32x16_bf16 v[82:97], v[200:203], v[180:183], v[82:97]
	ds_read_b128 v[200:203], v211 offset:39936
	s_waitcnt lgkmcnt(1)
	v_mfma_f32_32x32x16_bf16 v[114:129], v[196:199], v[184:187], v[114:129]
	s_waitcnt lgkmcnt(0)
	v_mfma_f32_32x32x16_bf16 v[114:129], v[200:203], v[180:183], v[114:129]
	s_waitcnt vmcnt(0)
	v_mov_b32_e32 v180, v194
	v_mov_b32_e32 v181, v195
	v_mov_b32_e32 v182, v190
	v_mov_b32_e32 v183, v191
	v_mov_b32_e32 v194, v188
	v_mov_b32_e32 v195, v189
	ds_write_b128 v216, v[192:195] offset:8192
	ds_write_b128 v216, v[180:183] offset:8704
	s_waitcnt lgkmcnt(0)
	s_barrier
; #define LAS __attribute__((address_space(3)))
; __device__ __forceinline__ void attn_wg_unit(const Args& args, int l, int u, LAS unsigned char* lds, int tid_in) {
;     ...
; #pragma unroll
;     for (int kt = 0; kt < 8; ++kt) {
;         if (kt < 7) { s0 = *(const u32x4*)(vsrc + 32 * (kt + 1)); s1 = *(const u32x4*)(vsrc + 32 * (kt + 1) + 8); }
;         const LAS unsigned char* cb = buf + (kt & 1) * 16384 + lane * 16;
; #pragma unroll
;         for (int dt = 0; dt < 8; ++dt)
; #pragma unroll
;             for (int s = 0; s < 2; ++s) { const bf16x8 vf = *(const LAS bf16x8*)(cb + (dt * 2 + s) * 1024); ot[dt] = __builtin_amdgcn_mfma_f32_32x32x16_bf16(vf, pf[kt][s], ot[dt], 0, 0, 0); }
;         if (kt < 7) {
;             LAS unsigned char* nb = buf + ((kt + 1) & 1) * 16384;
;             *(LAS u32x4*)(nb + vdst) = (u32x4){s0.x, s0.y, s1.x, s1.y}; *(LAS u32x4*)(nb + vdst + 512) = (u32x4){s0.z, s0.w, s1.z, s1.w};
;         }
;         __syncthreads();
;     }
	global_load_dwordx4 v[180:183], v[214:215], off offset:208
	global_load_dwordx4 v[184:187], v[214:215], off offset:192
	ds_read_b128 v[188:191], v211 offset:8192
	ds_read_b128 v[192:195], v211 offset:9216
	ds_read_b128 v[196:199], v211 offset:10240
	ds_read_b128 v[200:203], v211 offset:11264
	s_waitcnt lgkmcnt(3)
	v_mfma_f32_32x32x16_bf16 v[2:17], v[188:191], v[176:179], v[2:17]
	ds_read_b128 v[188:191], v211 offset:12288
	s_waitcnt lgkmcnt(3)
	v_mfma_f32_32x32x16_bf16 v[2:17], v[192:195], v[172:175], v[2:17]
	ds_read_b128 v[192:195], v211 offset:13312
	s_waitcnt lgkmcnt(3)
	v_mfma_f32_32x32x16_bf16 v[50:65], v[196:199], v[176:179], v[50:65]
	ds_read_b128 v[196:199], v211 offset:14336
	s_waitcnt lgkmcnt(3)
	v_mfma_f32_32x32x16_bf16 v[50:65], v[200:203], v[172:175], v[50:65]
	ds_read_b128 v[200:203], v211 offset:15360
	s_waitcnt lgkmcnt(3)
	v_mfma_f32_32x32x16_bf16 v[34:49], v[188:191], v[176:179], v[34:49]
	ds_read_b128 v[188:191], v211 offset:16384
	s_waitcnt lgkmcnt(3)
	v_mfma_f32_32x32x16_bf16 v[34:49], v[192:195], v[172:175], v[34:49]
	ds_read_b128 v[192:195], v211 offset:17408
	s_waitcnt lgkmcnt(3)
	v_mfma_f32_32x32x16_bf16 v[18:33], v[196:199], v[176:179], v[18:33]
	ds_read_b128 v[196:199], v211 offset:18432
	s_waitcnt lgkmcnt(3)
	v_mfma_f32_32x32x16_bf16 v[18:33], v[200:203], v[172:175], v[18:33]
	ds_read_b128 v[200:203], v211 offset:19456
	s_waitcnt lgkmcnt(3)
	v_mfma_f32_32x32x16_bf16 v[66:81], v[188:191], v[176:179], v[66:81]
	ds_read_b128 v[188:191], v211 offset:20480
	s_waitcnt lgkmcnt(3)
	v_mfma_f32_32x32x16_bf16 v[66:81], v[192:195], v[172:175], v[66:81]
	ds_read_b128 v[192:195], v211 offset:21504
	s_waitcnt lgkmcnt(3)
	v_mfma_f32_32x32x16_bf16 v[98:113], v[196:199], v[176:179], v[98:113]
	ds_read_b128 v[196:199], v211 offset:22528
	s_waitcnt lgkmcnt(3)
	v_mfma_f32_32x32x16_bf16 v[98:113], v[200:203], v[172:175], v[98:113]
	ds_read_b128 v[200:203], v211 offset:23552
	s_waitcnt lgkmcnt(3)
	v_mfma_f32_32x32x16_bf16 v[82:97], v[188:191], v[176:179], v[82:97]
	s_waitcnt lgkmcnt(2)
	v_mfma_f32_32x32x16_bf16 v[82:97], v[192:195], v[172:175], v[82:97]
	s_waitcnt lgkmcnt(1)
	v_mfma_f32_32x32x16_bf16 v[114:129], v[196:199], v[176:179], v[114:129]
	s_waitcnt lgkmcnt(0)
	v_mfma_f32_32x32x16_bf16 v[114:129], v[200:203], v[172:175], v[114:129]
	s_waitcnt vmcnt(0)
	v_mov_b32_e32 v172, v186
	v_mov_b32_e32 v173, v187
	v_mov_b32_e32 v174, v182
	v_mov_b32_e32 v175, v183
	v_mov_b32_e32 v186, v180
	v_mov_b32_e32 v187, v181
	ds_write_b128 v216, v[184:187] offset:24576
	ds_write_b128 v216, v[172:175] offset:25088
	s_waitcnt lgkmcnt(0)
	s_barrier
	global_load_dwordx4 v[172:175], v[214:215], off offset:272
	global_load_dwordx4 v[176:179], v[214:215], off offset:256
	ds_read_b128 v[180:183], v211 offset:24576
	ds_read_b128 v[184:187], v211 offset:25600
	ds_read_b128 v[188:191], v211 offset:26624
	ds_read_b128 v[192:195], v211 offset:27648
	ds_read_b128 v[196:199], v211 offset:28672
	ds_read_b128 v[200:203], v211 offset:29696
	s_waitcnt lgkmcnt(5)
	v_mfma_f32_32x32x16_bf16 v[2:17], v[180:183], v[168:171], v[2:17]
	ds_read_b128 v[180:183], v211 offset:30720
	s_waitcnt lgkmcnt(5)
	v_mfma_f32_32x32x16_bf16 v[2:17], v[184:187], v[164:167], v[2:17]
	ds_read_b128 v[184:187], v211 offset:31744
	s_waitcnt lgkmcnt(5)
	v_mfma_f32_32x32x16_bf16 v[50:65], v[188:191], v[168:171], v[50:65]
	ds_read_b128 v[188:191], v211 offset:32768
	s_waitcnt lgkmcnt(5)
	v_mfma_f32_32x32x16_bf16 v[50:65], v[192:195], v[164:167], v[50:65]
	ds_read_b128 v[192:195], v211 offset:33792
	s_waitcnt lgkmcnt(5)
	v_mfma_f32_32x32x16_bf16 v[34:49], v[196:199], v[168:171], v[34:49]
	ds_read_b128 v[196:199], v211 offset:34816
	s_waitcnt lgkmcnt(5)
	v_mfma_f32_32x32x16_bf16 v[34:49], v[200:203], v[164:167], v[34:49]
	ds_read_b128 v[200:203], v211 offset:35840
	s_waitcnt lgkmcnt(5)
	v_mfma_f32_32x32x16_bf16 v[18:33], v[180:183], v[168:171], v[18:33]
	ds_read_b128 v[180:183], v211 offset:36864
	s_waitcnt lgkmcnt(5)
	v_mfma_f32_32x32x16_bf16 v[18:33], v[184:187], v[164:167], v[18:33]
	ds_read_b128 v[184:187], v211 offset:37888
	s_waitcnt lgkmcnt(5)
	v_mfma_f32_32x32x16_bf16 v[66:81], v[188:191], v[168:171], v[66:81]
	ds_read_b128 v[188:191], v211 offset:38912
	s_waitcnt lgkmcnt(5)
	v_mfma_f32_32x32x16_bf16 v[66:81], v[192:195], v[164:167], v[66:81]
	ds_read_b128 v[192:195], v211 offset:39936
	s_waitcnt lgkmcnt(5)
	v_mfma_f32_32x32x16_bf16 v[98:113], v[196:199], v[168:171], v[98:113]
	s_waitcnt lgkmcnt(4)
	v_mfma_f32_32x32x16_bf16 v[98:113], v[200:203], v[164:167], v[98:113]
	s_waitcnt lgkmcnt(3)
	v_mfma_f32_32x32x16_bf16 v[82:97], v[180:183], v[168:171], v[82:97]
	s_waitcnt lgkmcnt(2)
	v_mfma_f32_32x32x16_bf16 v[82:97], v[184:187], v[164:167], v[82:97]
	s_waitcnt lgkmcnt(1)
	v_mfma_f32_32x32x16_bf16 v[114:129], v[188:191], v[168:171], v[114:129]
	s_waitcnt lgkmcnt(0)
	v_mfma_f32_32x32x16_bf16 v[114:129], v[192:195], v[164:167], v[114:129]
	s_waitcnt vmcnt(0)
	v_mov_b32_e32 v164, v178
	v_mov_b32_e32 v165, v179
	v_mov_b32_e32 v166, v174
	v_mov_b32_e32 v167, v175
	v_mov_b32_e32 v178, v172
	v_mov_b32_e32 v179, v173
	ds_write_b128 v216, v[176:179] offset:8192
	ds_write_b128 v216, v[164:167] offset:8704
	s_waitcnt lgkmcnt(0)
	s_barrier
; #define LAS __attribute__((address_space(3)))
; __device__ __forceinline__ void attn_wg_unit(const Args& args, int l, int u, LAS unsigned char* lds, int tid_in) {
;     ...
; #pragma unroll
;     for (int kt = 0; kt < 8; ++kt) {
;         if (kt < 7) { s0 = *(const u32x4*)(vsrc + 32 * (kt + 1)); s1 = *(const u32x4*)(vsrc + 32 * (kt + 1) + 8); }
;         const LAS unsigned char* cb = buf + (kt & 1) * 16384 + lane * 16;
; #pragma unroll
;         for (int dt = 0; dt < 8; ++dt)
; #pragma unroll
;             for (int s = 0; s < 2; ++s) { const bf16x8 vf = *(const LAS bf16x8*)(cb + (dt * 2 + s) * 1024); ot[dt] = __builtin_amdgcn_mfma_f32_32x32x16_bf16(vf, pf[kt][s], ot[dt], 0, 0, 0); }
;         if (kt < 7) {
;             LAS unsigned char* nb = buf + ((kt + 1) & 1) * 16384;
;             *(LAS u32x4*)(nb + vdst) = (u32x4){s0.x, s0.y, s1.x, s1.y}; *(LAS u32x4*)(nb + vdst + 512) = (u32x4){s0.z, s0.w, s1.z, s1.w};
;         }
;         __syncthreads();
;     }
	global_load_dwordx4 v[164:167], v[214:215], off offset:336
	global_load_dwordx4 v[168:171], v[214:215], off offset:320
	ds_read_b128 v[172:175], v211 offset:8192
	ds_read_b128 v[176:179], v211 offset:9216
	ds_read_b128 v[180:183], v211 offset:10240
	ds_read_b128 v[184:187], v211 offset:11264
	ds_read_b128 v[188:191], v211 offset:12288
	ds_read_b128 v[192:195], v211 offset:13312
	s_waitcnt lgkmcnt(5)
	v_mfma_f32_32x32x16_bf16 v[2:17], v[172:175], v[160:163], v[2:17]
	ds_read_b128 v[196:199], v211 offset:14336
	s_waitcnt lgkmcnt(5)
	v_mfma_f32_32x32x16_bf16 v[2:17], v[176:179], v[156:159], v[2:17]
	ds_read_b128 v[200:203], v211 offset:15360
	s_waitcnt lgkmcnt(5)
	v_mfma_f32_32x32x16_bf16 v[50:65], v[180:183], v[160:163], v[50:65]
	ds_read_b128 v[172:175], v211 offset:16384
	s_waitcnt lgkmcnt(5)
	v_mfma_f32_32x32x16_bf16 v[50:65], v[184:187], v[156:159], v[50:65]
	ds_read_b128 v[176:179], v211 offset:17408
	s_waitcnt lgkmcnt(5)
	v_mfma_f32_32x32x16_bf16 v[34:49], v[188:191], v[160:163], v[34:49]
	ds_read_b128 v[180:183], v211 offset:18432
	s_waitcnt lgkmcnt(5)
	v_mfma_f32_32x32x16_bf16 v[34:49], v[192:195], v[156:159], v[34:49]
	ds_read_b128 v[184:187], v211 offset:19456
	s_waitcnt lgkmcnt(5)
	v_mfma_f32_32x32x16_bf16 v[18:33], v[196:199], v[160:163], v[18:33]
	ds_read_b128 v[188:191], v211 offset:20480
	s_waitcnt lgkmcnt(5)
	v_mfma_f32_32x32x16_bf16 v[18:33], v[200:203], v[156:159], v[18:33]
	ds_read_b128 v[192:195], v211 offset:21504
	s_waitcnt lgkmcnt(5)
	v_mfma_f32_32x32x16_bf16 v[66:81], v[172:175], v[160:163], v[66:81]
	ds_read_b128 v[196:199], v211 offset:22528
	s_waitcnt lgkmcnt(5)
	v_mfma_f32_32x32x16_bf16 v[66:81], v[176:179], v[156:159], v[66:81]
	ds_read_b128 v[200:203], v211 offset:23552
	s_waitcnt lgkmcnt(5)
	v_mfma_f32_32x32x16_bf16 v[98:113], v[180:183], v[160:163], v[98:113]
	s_waitcnt lgkmcnt(4)
	v_mfma_f32_32x32x16_bf16 v[98:113], v[184:187], v[156:159], v[98:113]
	s_waitcnt lgkmcnt(3)
	v_mfma_f32_32x32x16_bf16 v[82:97], v[188:191], v[160:163], v[82:97]
	s_waitcnt lgkmcnt(2)
	v_mfma_f32_32x32x16_bf16 v[82:97], v[192:195], v[156:159], v[82:97]
	s_waitcnt lgkmcnt(1)
	v_mfma_f32_32x32x16_bf16 v[114:129], v[196:199], v[160:163], v[114:129]
	s_waitcnt lgkmcnt(0)
	v_mfma_f32_32x32x16_bf16 v[114:129], v[200:203], v[156:159], v[114:129]
	s_waitcnt vmcnt(0)
	v_mov_b32_e32 v156, v170
	v_mov_b32_e32 v157, v171
	v_mov_b32_e32 v158, v166
	v_mov_b32_e32 v159, v167
	v_mov_b32_e32 v170, v164
	v_mov_b32_e32 v171, v165
	ds_write_b128 v216, v[168:171] offset:24576
	ds_write_b128 v216, v[156:159] offset:25088
	s_waitcnt lgkmcnt(0)
	s_barrier
	global_load_dwordx4 v[156:159], v[214:215], off offset:400
	global_load_dwordx4 v[160:163], v[214:215], off offset:384
	ds_read_b128 v[164:167], v211 offset:24576
	ds_read_b128 v[168:171], v211 offset:25600
	ds_read_b128 v[172:175], v211 offset:26624
	ds_read_b128 v[176:179], v211 offset:27648
	ds_read_b128 v[180:183], v211 offset:28672
	ds_read_b128 v[184:187], v211 offset:29696
	s_waitcnt lgkmcnt(5)
	v_mfma_f32_32x32x16_bf16 v[2:17], v[164:167], v[152:155], v[2:17]
	ds_read_b128 v[188:191], v211 offset:30720
	s_waitcnt lgkmcnt(5)
	v_mfma_f32_32x32x16_bf16 v[2:17], v[168:171], v[148:151], v[2:17]
	ds_read_b128 v[192:195], v211 offset:31744
	s_waitcnt lgkmcnt(5)
	v_mfma_f32_32x32x16_bf16 v[50:65], v[172:175], v[152:155], v[50:65]
	ds_read_b128 v[164:167], v211 offset:32768
	s_waitcnt lgkmcnt(5)
	v_mfma_f32_32x32x16_bf16 v[50:65], v[176:179], v[148:151], v[50:65]
	ds_read_b128 v[168:171], v211 offset:33792
	s_waitcnt lgkmcnt(5)
	v_mfma_f32_32x32x16_bf16 v[34:49], v[180:183], v[152:155], v[34:49]
	ds_read_b128 v[172:175], v211 offset:34816
	s_waitcnt lgkmcnt(5)
	v_mfma_f32_32x32x16_bf16 v[34:49], v[184:187], v[148:151], v[34:49]
	ds_read_b128 v[176:179], v211 offset:35840
	s_waitcnt lgkmcnt(5)
	v_mfma_f32_32x32x16_bf16 v[18:33], v[188:191], v[152:155], v[18:33]
	ds_read_b128 v[180:183], v211 offset:36864
	s_waitcnt lgkmcnt(5)
	v_mfma_f32_32x32x16_bf16 v[18:33], v[192:195], v[148:151], v[18:33]
	ds_read_b128 v[184:187], v211 offset:37888
	s_waitcnt lgkmcnt(5)
	v_mfma_f32_32x32x16_bf16 v[66:81], v[164:167], v[152:155], v[66:81]
	ds_read_b128 v[188:191], v211 offset:38912
	s_waitcnt lgkmcnt(5)
	v_mfma_f32_32x32x16_bf16 v[66:81], v[168:171], v[148:151], v[66:81]
	ds_read_b128 v[192:195], v211 offset:39936
	s_waitcnt lgkmcnt(5)
	v_mfma_f32_32x32x16_bf16 v[98:113], v[172:175], v[152:155], v[98:113]
	s_waitcnt lgkmcnt(4)
	v_mfma_f32_32x32x16_bf16 v[98:113], v[176:179], v[148:151], v[98:113]
	s_waitcnt lgkmcnt(3)
	v_mfma_f32_32x32x16_bf16 v[82:97], v[180:183], v[152:155], v[82:97]
	s_waitcnt lgkmcnt(2)
	v_mfma_f32_32x32x16_bf16 v[82:97], v[184:187], v[148:151], v[82:97]
	s_waitcnt lgkmcnt(1)
	v_mfma_f32_32x32x16_bf16 v[114:129], v[188:191], v[152:155], v[114:129]
	s_waitcnt lgkmcnt(0)
	v_mfma_f32_32x32x16_bf16 v[114:129], v[192:195], v[148:151], v[114:129]
	s_waitcnt vmcnt(0)
	v_mov_b32_e32 v148, v162
	v_mov_b32_e32 v149, v163
	v_mov_b32_e32 v150, v158
	v_mov_b32_e32 v151, v159
	v_mov_b32_e32 v162, v156
	v_mov_b32_e32 v163, v157
	ds_write_b128 v216, v[160:163] offset:8192
	ds_write_b128 v216, v[148:151] offset:8704
	s_waitcnt lgkmcnt(0)
	s_barrier
; #define LAS __attribute__((address_space(3)))
; __device__ __forceinline__ void attn_wg_unit(const Args& args, int l, int u, LAS unsigned char* lds, int tid_in) {
;     ...
; #pragma unroll
;     for (int kt = 0; kt < 8; ++kt) {
;         if (kt < 7) { s0 = *(const u32x4*)(vsrc + 32 * (kt + 1)); s1 = *(const u32x4*)(vsrc + 32 * (kt + 1) + 8); }
;         const LAS unsigned char* cb = buf + (kt & 1) * 16384 + lane * 16;
; #pragma unroll
;         for (int dt = 0; dt < 8; ++dt)
; #pragma unroll
;             for (int s = 0; s < 2; ++s) { const bf16x8 vf = *(const LAS bf16x8*)(cb + (dt * 2 + s) * 1024); ot[dt] = __builtin_amdgcn_mfma_f32_32x32x16_bf16(vf, pf[kt][s], ot[dt], 0, 0, 0); }
;         if (kt < 7) {
;             LAS unsigned char* nb = buf + ((kt + 1) & 1) * 16384;
;             *(LAS u32x4*)(nb + vdst) = (u32x4){s0.x, s0.y, s1.x, s1.y}; *(LAS u32x4*)(nb + vdst + 512) = (u32x4){s0.z, s0.w, s1.z, s1.w};
;         }
;         __syncthreads();
;     }
	global_load_dwordx4 v[148:151], v[214:215], off offset:464
	global_load_dwordx4 v[152:155], v[214:215], off offset:448
	ds_read_b128 v[156:159], v211 offset:8192
	ds_read_b128 v[160:163], v211 offset:9216
	ds_read_b128 v[164:167], v211 offset:10240
	ds_read_b128 v[168:171], v211 offset:11264
	ds_read_b128 v[172:175], v211 offset:12288
	ds_read_b128 v[176:179], v211 offset:13312
	s_waitcnt lgkmcnt(5)
	v_mfma_f32_32x32x16_bf16 v[2:17], v[156:159], v[136:139], v[2:17]
	ds_read_b128 v[180:183], v211 offset:14336
	s_waitcnt lgkmcnt(5)
	v_mfma_f32_32x32x16_bf16 v[2:17], v[160:163], v[132:135], v[2:17]
	ds_read_b128 v[184:187], v211 offset:15360
	s_waitcnt lgkmcnt(5)
	v_mfma_f32_32x32x16_bf16 v[50:65], v[164:167], v[136:139], v[50:65]
	ds_read_b128 v[156:159], v211 offset:16384
	s_waitcnt lgkmcnt(5)
	v_mfma_f32_32x32x16_bf16 v[50:65], v[168:171], v[132:135], v[50:65]
	ds_read_b128 v[160:163], v211 offset:17408
	s_waitcnt lgkmcnt(5)
	v_mfma_f32_32x32x16_bf16 v[34:49], v[172:175], v[136:139], v[34:49]
	ds_read_b128 v[164:167], v211 offset:18432
	s_waitcnt lgkmcnt(5)
	v_mfma_f32_32x32x16_bf16 v[34:49], v[176:179], v[132:135], v[34:49]
	ds_read_b128 v[168:171], v211 offset:19456
	s_waitcnt lgkmcnt(5)
	v_mfma_f32_32x32x16_bf16 v[18:33], v[180:183], v[136:139], v[18:33]
	ds_read_b128 v[172:175], v211 offset:20480
	s_waitcnt lgkmcnt(5)
	v_mfma_f32_32x32x16_bf16 v[18:33], v[184:187], v[132:135], v[18:33]
	ds_read_b128 v[176:179], v211 offset:21504
	s_waitcnt lgkmcnt(5)
	v_mfma_f32_32x32x16_bf16 v[66:81], v[156:159], v[136:139], v[66:81]
	ds_read_b128 v[180:183], v211 offset:22528
	s_waitcnt lgkmcnt(5)
	v_mfma_f32_32x32x16_bf16 v[66:81], v[160:163], v[132:135], v[66:81]
	ds_read_b128 v[184:187], v211 offset:23552
	s_waitcnt lgkmcnt(5)
	v_mfma_f32_32x32x16_bf16 v[98:113], v[164:167], v[136:139], v[98:113]
	s_waitcnt lgkmcnt(4)
	v_mfma_f32_32x32x16_bf16 v[98:113], v[168:171], v[132:135], v[98:113]
	s_waitcnt lgkmcnt(3)
	v_mfma_f32_32x32x16_bf16 v[82:97], v[172:175], v[136:139], v[82:97]
	s_waitcnt lgkmcnt(2)
	v_mfma_f32_32x32x16_bf16 v[82:97], v[176:179], v[132:135], v[82:97]
	s_waitcnt lgkmcnt(1)
	v_mfma_f32_32x32x16_bf16 v[114:129], v[180:183], v[136:139], v[114:129]
	s_waitcnt lgkmcnt(0)
	v_mfma_f32_32x32x16_bf16 v[114:129], v[184:187], v[132:135], v[114:129]
	s_waitcnt vmcnt(0)
	v_mov_b32_e32 v132, v154
	v_mov_b32_e32 v133, v155
	v_mov_b32_e32 v134, v150
	v_mov_b32_e32 v135, v151
	v_mov_b32_e32 v154, v148
	v_mov_b32_e32 v155, v149
	ds_write_b128 v216, v[152:155] offset:24576
	ds_write_b128 v216, v[132:135] offset:25088
	s_waitcnt lgkmcnt(0)
	s_barrier
	ds_read_b128 v[132:135], v211 offset:24576
	ds_read_b128 v[136:139], v211 offset:25600
	ds_read_b128 v[148:151], v211 offset:26624
	ds_read_b128 v[152:155], v211 offset:27648
	ds_read_b128 v[156:159], v211 offset:28672
	ds_read_b128 v[160:163], v211 offset:29696
	s_waitcnt lgkmcnt(5)
	v_mfma_f32_32x32x16_bf16 v[2:17], v[132:135], v[140:143], v[2:17]
	ds_read_b128 v[164:167], v211 offset:30720
	s_waitcnt lgkmcnt(5)
	v_mfma_f32_32x32x16_bf16 v[2:17], v[136:139], v[144:147], v[2:17]
	ds_read_b128 v[168:171], v211 offset:31744
	s_waitcnt lgkmcnt(5)
	v_mfma_f32_32x32x16_bf16 v[50:65], v[148:151], v[140:143], v[50:65]
	ds_read_b128 v[132:135], v211 offset:32768
	s_waitcnt lgkmcnt(5)
	v_mfma_f32_32x32x16_bf16 v[50:65], v[152:155], v[144:147], v[50:65]
	ds_read_b128 v[136:139], v211 offset:33792
	s_waitcnt lgkmcnt(5)
	v_mfma_f32_32x32x16_bf16 v[34:49], v[156:159], v[140:143], v[34:49]
	ds_read_b128 v[148:151], v211 offset:34816
	s_waitcnt lgkmcnt(5)
	v_mfma_f32_32x32x16_bf16 v[34:49], v[160:163], v[144:147], v[34:49]
	ds_read_b128 v[152:155], v211 offset:35840
	s_waitcnt lgkmcnt(5)
	v_mfma_f32_32x32x16_bf16 v[18:33], v[164:167], v[140:143], v[18:33]
	ds_read_b128 v[156:159], v211 offset:36864
	s_waitcnt lgkmcnt(5)
	v_mfma_f32_32x32x16_bf16 v[18:33], v[168:171], v[144:147], v[18:33]
	ds_read_b128 v[160:163], v211 offset:37888
	s_waitcnt lgkmcnt(5)
	v_mfma_f32_32x32x16_bf16 v[66:81], v[132:135], v[140:143], v[66:81]
	ds_read_b128 v[164:167], v211 offset:38912
	s_waitcnt lgkmcnt(5)
	v_mfma_f32_32x32x16_bf16 v[66:81], v[136:139], v[144:147], v[66:81]
	ds_read_b128 v[168:171], v211 offset:39936
	s_waitcnt lgkmcnt(5)
	v_mfma_f32_32x32x16_bf16 v[98:113], v[148:151], v[140:143], v[98:113]
	s_waitcnt lgkmcnt(4)
	v_mfma_f32_32x32x16_bf16 v[98:113], v[152:155], v[144:147], v[98:113]
	s_waitcnt lgkmcnt(3)
	v_mfma_f32_32x32x16_bf16 v[82:97], v[156:159], v[140:143], v[82:97]
	s_waitcnt lgkmcnt(2)
	v_mfma_f32_32x32x16_bf16 v[82:97], v[160:163], v[144:147], v[82:97]
	s_waitcnt lgkmcnt(1)
	v_mfma_f32_32x32x16_bf16 v[114:129], v[164:167], v[140:143], v[114:129]
	s_waitcnt lgkmcnt(0)
	s_barrier
; #define LAS __attribute__((address_space(3)))
; __device__ __forceinline__ unsigned cvtpk(float lo, float hi) { f32x2 v = {lo, hi}; bf16x2_t b = __builtin_convertvector(v, bf16x2_t); return __builtin_bit_cast(unsigned, b); }
; __device__ __forceinline__ void attn_wg_unit(const Args& args, int l, int u, LAS unsigned char* lds, int tid_in) {
;     ...
;             for (int s = 0; s < 2; ++s) { const bf16x8 vf = *(const LAS bf16x8*)(cb + (dt * 2 + s) * 1024); ot[dt] = __builtin_amdgcn_mfma_f32_32x32x16_bf16(vf, pf[kt][s], ot[dt], 0, 0, 0); }
;         if (kt < 7) {
;             LAS unsigned char* nb = buf + ((kt + 1) & 1) * 16384;
;             *(LAS u32x4*)(nb + vdst) = (u32x4){s0.x, s0.y, s1.x, s1.y}; *(LAS u32x4*)(nb + vdst + 512) = (u32x4){s0.z, s0.w, s1.z, s1.w};
;         }
;         __syncthreads();
;     }
;     bf16_t* op = AMEM + (size_t)(row0 + r32) * MW + head * MHD;
; #pragma unroll
;     for (int dt = 0; dt < 8; ++dt)
; #pragma unroll
;         for (int ig = 0; ig < 4; ++ig) {
;             u32x2 w; w.x = cvtpk(ot[dt][4 * ig] * inv, ot[dt][4 * ig + 1] * inv); w.y = cvtpk(ot[dt][4 * ig + 2] * inv, ot[dt][4 * ig + 3] * inv);
;             *(u32x2*)(op + 32 * dt + 8 * ig + 4 * hh) = w;
;         }
	v_mfma_f32_32x32x16_bf16 v[114:129], v[168:171], v[144:147], v[114:129]
	v_add_f32_e32 v132, v217, v218
	v_rcp_f32_e32 v132, v132
	v_lshlrev_b64 v[134:135], 11, v[212:213]
	v_lshl_add_u64 v[134:135], s[90:91], 0, v[134:135]
	v_lshl_add_u64 v[134:135], v[134:135], 0, s[80:81]
	v_pk_mul_f32 v[2:3], v[132:133], v[2:3] op_sel_hi:[0,1]
	v_pk_mul_f32 v[4:5], v[132:133], v[4:5] op_sel_hi:[0,1]
	v_lshl_add_u64 v[134:135], v[134:135], 0, v[130:131]
	v_cvt_pk_bf16_f32 v2, v2, v3
	v_cvt_pk_bf16_f32 v3, v4, v5
	global_store_dwordx2 v[134:135], v[2:3], off
	v_pk_mul_f32 v[2:3], v[132:133], v[6:7] op_sel_hi:[0,1]
	v_pk_mul_f32 v[4:5], v[132:133], v[8:9] op_sel_hi:[0,1]
	v_cvt_pk_bf16_f32 v2, v2, v3
	v_cvt_pk_bf16_f32 v3, v4, v5
	global_store_dwordx2 v[134:135], v[2:3], off offset:16
	v_pk_mul_f32 v[2:3], v[132:133], v[10:11] op_sel_hi:[0,1]
	v_pk_mul_f32 v[4:5], v[132:133], v[12:13] op_sel_hi:[0,1]
	v_cvt_pk_bf16_f32 v2, v2, v3
	v_cvt_pk_bf16_f32 v3, v4, v5
	global_store_dwordx2 v[134:135], v[2:3], off offset:32
	v_pk_mul_f32 v[2:3], v[132:133], v[14:15] op_sel_hi:[0,1]
	v_pk_mul_f32 v[4:5], v[132:133], v[16:17] op_sel_hi:[0,1]
	v_cvt_pk_bf16_f32 v2, v2, v3
	v_cvt_pk_bf16_f32 v3, v4, v5
	global_store_dwordx2 v[134:135], v[2:3], off offset:48
	v_pk_mul_f32 v[2:3], v[132:133], v[50:51] op_sel_hi:[0,1]
	v_pk_mul_f32 v[4:5], v[132:133], v[52:53] op_sel_hi:[0,1]
	v_cvt_pk_bf16_f32 v2, v2, v3
	v_cvt_pk_bf16_f32 v3, v4, v5
	global_store_dwordx2 v[134:135], v[2:3], off offset:64
	v_pk_mul_f32 v[2:3], v[132:133], v[54:55] op_sel_hi:[0,1]
	v_pk_mul_f32 v[4:5], v[132:133], v[56:57] op_sel_hi:[0,1]
	v_cvt_pk_bf16_f32 v2, v2, v3
	v_cvt_pk_bf16_f32 v3, v4, v5
	global_store_dwordx2 v[134:135], v[2:3], off offset:80
	v_pk_mul_f32 v[2:3], v[132:133], v[58:59] op_sel_hi:[0,1]
	v_pk_mul_f32 v[4:5], v[132:133], v[60:61] op_sel_hi:[0,1]
	v_cvt_pk_bf16_f32 v2, v2, v3
	v_cvt_pk_bf16_f32 v3, v4, v5
	global_store_dwordx2 v[134:135], v[2:3], off offset:96
	v_pk_mul_f32 v[2:3], v[132:133], v[62:63] op_sel_hi:[0,1]
	v_pk_mul_f32 v[4:5], v[132:133], v[64:65] op_sel_hi:[0,1]
	v_cvt_pk_bf16_f32 v2, v2, v3
	v_cvt_pk_bf16_f32 v3, v4, v5
	global_store_dwordx2 v[134:135], v[2:3], off offset:112
	v_pk_mul_f32 v[2:3], v[132:133], v[34:35] op_sel_hi:[0,1]
	v_pk_mul_f32 v[4:5], v[132:133], v[36:37] op_sel_hi:[0,1]
	v_cvt_pk_bf16_f32 v2, v2, v3
	v_cvt_pk_bf16_f32 v3, v4, v5
	global_store_dwordx2 v[134:135], v[2:3], off offset:128
	v_pk_mul_f32 v[2:3], v[132:133], v[38:39] op_sel_hi:[0,1]
	v_pk_mul_f32 v[4:5], v[132:133], v[40:41] op_sel_hi:[0,1]
	v_cvt_pk_bf16_f32 v2, v2, v3
	v_cvt_pk_bf16_f32 v3, v4, v5
	global_store_dwordx2 v[134:135], v[2:3], off offset:144
	v_pk_mul_f32 v[2:3], v[132:133], v[42:43] op_sel_hi:[0,1]
	v_pk_mul_f32 v[4:5], v[132:133], v[44:45] op_sel_hi:[0,1]
	v_cvt_pk_bf16_f32 v2, v2, v3
	v_cvt_pk_bf16_f32 v3, v4, v5
	global_store_dwordx2 v[134:135], v[2:3], off offset:160
	v_pk_mul_f32 v[2:3], v[132:133], v[46:47] op_sel_hi:[0,1]
	v_pk_mul_f32 v[4:5], v[132:133], v[48:49] op_sel_hi:[0,1]
	v_cvt_pk_bf16_f32 v2, v2, v3
	v_cvt_pk_bf16_f32 v3, v4, v5
	global_store_dwordx2 v[134:135], v[2:3], off offset:176
	v_pk_mul_f32 v[2:3], v[132:133], v[18:19] op_sel_hi:[0,1]
	v_pk_mul_f32 v[4:5], v[132:133], v[20:21] op_sel_hi:[0,1]
	v_cvt_pk_bf16_f32 v2, v2, v3
	v_cvt_pk_bf16_f32 v3, v4, v5
	global_store_dwordx2 v[134:135], v[2:3], off offset:192
	v_pk_mul_f32 v[2:3], v[132:133], v[22:23] op_sel_hi:[0,1]
	v_pk_mul_f32 v[4:5], v[132:133], v[24:25] op_sel_hi:[0,1]
	v_cvt_pk_bf16_f32 v2, v2, v3
	v_cvt_pk_bf16_f32 v3, v4, v5
	global_store_dwordx2 v[134:135], v[2:3], off offset:208
	v_pk_mul_f32 v[2:3], v[132:133], v[26:27] op_sel_hi:[0,1]
	v_pk_mul_f32 v[4:5], v[132:133], v[28:29] op_sel_hi:[0,1]
	v_cvt_pk_bf16_f32 v2, v2, v3
	v_cvt_pk_bf16_f32 v3, v4, v5
	global_store_dwordx2 v[134:135], v[2:3], off offset:224
	v_pk_mul_f32 v[2:3], v[132:133], v[30:31] op_sel_hi:[0,1]
	v_pk_mul_f32 v[4:5], v[132:133], v[32:33] op_sel_hi:[0,1]
; __device__ __forceinline__ unsigned cvtpk(float lo, float hi) { f32x2 v = {lo, hi}; bf16x2_t b = __builtin_convertvector(v, bf16x2_t); return __builtin_bit_cast(unsigned, b); }
; __device__ __forceinline__ void attn_wg_unit(const Args& args, int l, int u, LAS unsigned char* lds, int tid_in) {
;     ...
;     bf16_t* op = AMEM + (size_t)(row0 + r32) * MW + head * MHD;
; #pragma unroll
;     for (int dt = 0; dt < 8; ++dt)
; #pragma unroll
;         for (int ig = 0; ig < 4; ++ig) {
;             u32x2 w; w.x = cvtpk(ot[dt][4 * ig] * inv, ot[dt][4 * ig + 1] * inv); w.y = cvtpk(ot[dt][4 * ig + 2] * inv, ot[dt][4 * ig + 3] * inv);
;             *(u32x2*)(op + 32 * dt + 8 * ig + 4 * hh) = w;
;         }
	v_cvt_pk_bf16_f32 v2, v2, v3
	v_cvt_pk_bf16_f32 v3, v4, v5
	global_store_dwordx2 v[134:135], v[2:3], off offset:240
	v_pk_mul_f32 v[2:3], v[132:133], v[66:67] op_sel_hi:[0,1]
	v_pk_mul_f32 v[4:5], v[132:133], v[68:69] op_sel_hi:[0,1]
	v_cvt_pk_bf16_f32 v2, v2, v3
	v_cvt_pk_bf16_f32 v3, v4, v5
	global_store_dwordx2 v[134:135], v[2:3], off offset:256
	v_pk_mul_f32 v[2:3], v[132:133], v[70:71] op_sel_hi:[0,1]
	v_pk_mul_f32 v[4:5], v[132:133], v[72:73] op_sel_hi:[0,1]
	v_cvt_pk_bf16_f32 v2, v2, v3
	v_cvt_pk_bf16_f32 v3, v4, v5
	global_store_dwordx2 v[134:135], v[2:3], off offset:272
	v_pk_mul_f32 v[2:3], v[132:133], v[74:75] op_sel_hi:[0,1]
	v_pk_mul_f32 v[4:5], v[132:133], v[76:77] op_sel_hi:[0,1]
	v_cvt_pk_bf16_f32 v2, v2, v3
	v_cvt_pk_bf16_f32 v3, v4, v5
	global_store_dwordx2 v[134:135], v[2:3], off offset:288
	v_pk_mul_f32 v[2:3], v[132:133], v[78:79] op_sel_hi:[0,1]
	v_pk_mul_f32 v[4:5], v[132:133], v[80:81] op_sel_hi:[0,1]
	v_cvt_pk_bf16_f32 v2, v2, v3
	v_cvt_pk_bf16_f32 v3, v4, v5
	global_store_dwordx2 v[134:135], v[2:3], off offset:304
	v_pk_mul_f32 v[2:3], v[132:133], v[98:99] op_sel_hi:[0,1]
	v_pk_mul_f32 v[4:5], v[132:133], v[100:101] op_sel_hi:[0,1]
	v_cvt_pk_bf16_f32 v2, v2, v3
	v_cvt_pk_bf16_f32 v3, v4, v5
	global_store_dwordx2 v[134:135], v[2:3], off offset:320
	v_pk_mul_f32 v[2:3], v[132:133], v[102:103] op_sel_hi:[0,1]
	v_pk_mul_f32 v[4:5], v[132:133], v[104:105] op_sel_hi:[0,1]
	v_cvt_pk_bf16_f32 v2, v2, v3
	v_cvt_pk_bf16_f32 v3, v4, v5
	global_store_dwordx2 v[134:135], v[2:3], off offset:336
	v_pk_mul_f32 v[2:3], v[132:133], v[106:107] op_sel_hi:[0,1]
	v_pk_mul_f32 v[4:5], v[132:133], v[108:109] op_sel_hi:[0,1]
	v_cvt_pk_bf16_f32 v2, v2, v3
	v_cvt_pk_bf16_f32 v3, v4, v5
	global_store_dwordx2 v[134:135], v[2:3], off offset:352
	v_pk_mul_f32 v[2:3], v[132:133], v[110:111] op_sel_hi:[0,1]
	v_pk_mul_f32 v[4:5], v[132:133], v[112:113] op_sel_hi:[0,1]
	v_cvt_pk_bf16_f32 v2, v2, v3
	v_cvt_pk_bf16_f32 v3, v4, v5
	global_store_dwordx2 v[134:135], v[2:3], off offset:368
	v_pk_mul_f32 v[2:3], v[132:133], v[82:83] op_sel_hi:[0,1]
	v_pk_mul_f32 v[4:5], v[132:133], v[84:85] op_sel_hi:[0,1]
	v_cvt_pk_bf16_f32 v2, v2, v3
	v_cvt_pk_bf16_f32 v3, v4, v5
	global_store_dwordx2 v[134:135], v[2:3], off offset:384
	v_pk_mul_f32 v[2:3], v[132:133], v[86:87] op_sel_hi:[0,1]
	v_pk_mul_f32 v[4:5], v[132:133], v[88:89] op_sel_hi:[0,1]
	v_cvt_pk_bf16_f32 v2, v2, v3
	v_cvt_pk_bf16_f32 v3, v4, v5
	global_store_dwordx2 v[134:135], v[2:3], off offset:400
	v_pk_mul_f32 v[2:3], v[132:133], v[90:91] op_sel_hi:[0,1]
	v_pk_mul_f32 v[4:5], v[132:133], v[92:93] op_sel_hi:[0,1]
	v_cvt_pk_bf16_f32 v2, v2, v3
	v_cvt_pk_bf16_f32 v3, v4, v5
	global_store_dwordx2 v[134:135], v[2:3], off offset:416
	v_pk_mul_f32 v[2:3], v[132:133], v[94:95] op_sel_hi:[0,1]
	v_pk_mul_f32 v[4:5], v[132:133], v[96:97] op_sel_hi:[0,1]
	v_cvt_pk_bf16_f32 v2, v2, v3
	v_cvt_pk_bf16_f32 v3, v4, v5
	global_store_dwordx2 v[134:135], v[2:3], off offset:432
	v_pk_mul_f32 v[2:3], v[132:133], v[114:115] op_sel_hi:[0,1]
	v_pk_mul_f32 v[4:5], v[132:133], v[116:117] op_sel_hi:[0,1]
	v_cvt_pk_bf16_f32 v2, v2, v3
	v_cvt_pk_bf16_f32 v3, v4, v5
	global_store_dwordx2 v[134:135], v[2:3], off offset:448
	v_pk_mul_f32 v[2:3], v[132:133], v[118:119] op_sel_hi:[0,1]
	v_pk_mul_f32 v[4:5], v[132:133], v[120:121] op_sel_hi:[0,1]
	v_cvt_pk_bf16_f32 v2, v2, v3
	v_cvt_pk_bf16_f32 v3, v4, v5
	global_store_dwordx2 v[134:135], v[2:3], off offset:464
	v_pk_mul_f32 v[2:3], v[132:133], v[122:123] op_sel_hi:[0,1]
	v_pk_mul_f32 v[4:5], v[132:133], v[124:125] op_sel_hi:[0,1]
	v_cvt_pk_bf16_f32 v2, v2, v3
	v_cvt_pk_bf16_f32 v3, v4, v5
	global_store_dwordx2 v[134:135], v[2:3], off offset:480
	v_pk_mul_f32 v[2:3], v[132:133], v[126:127] op_sel_hi:[0,1]
	v_pk_mul_f32 v[4:5], v[132:133], v[128:129] op_sel_hi:[0,1]
	v_cvt_pk_bf16_f32 v2, v2, v3
	v_cvt_pk_bf16_f32 v3, v4, v5
	global_store_dwordx2 v[134:135], v[2:3], off offset:496
	s_cbranch_scc0 .LBB0_646
